# attention: s_setprio 1/0 around each MFMA cluster (independent waves, two per SIMD)
# speedup vs baseline: 1.0019x; 1.0019x over previous
.LBB0_349:
	v_lshl_add_u64 v[34:35], v[152:153], 0, s[34:35]
	s_mov_b32 s0, 0x11708000
	v_add_co_u32_e32 v120, vcc, s0, v34
	s_mov_b32 s0, 0x1170c000
	s_nop 0
	v_addc_co_u32_e32 v121, vcc, 0, v35, vcc
	v_add_co_u32_e32 v34, vcc, s0, v34
	v_lshl_add_u64 v[38:39], v[154:155], 0, s[34:35]
	s_nop 0
	v_addc_co_u32_e32 v35, vcc, 0, v35, vcc
	global_load_dwordx4 v[136:139], v[120:121], off
	global_load_dwordx4 v[140:143], v[120:121], off offset:1024
	global_load_dwordx4 v[148:151], v[34:35], off
	global_load_dwordx4 v[144:147], v[34:35], off offset:1024
	s_nop 0
	global_load_dwordx4 v[120:123], v[38:39], off offset:-2048
	global_load_dwordx4 v[124:127], v[38:39], off offset:-1024
	global_load_dwordx4 v[128:131], v[38:39], off
	global_load_dwordx4 v[132:135], v[38:39], off offset:1024
	ds_read_b128 v[214:217], v168 offset:20480
	ds_read_b128 v[218:221], v168 offset:21504
	ds_read_b32 v222, v212 offset:128
	ds_read_b32 v246, v212 offset:192
	ds_read_b32 v223, v212 offset:132
	ds_read_b32 v247, v212 offset:196
	ds_read_b32 v224, v212 offset:136
	ds_read_b32 v248, v212 offset:200
	ds_read_b32 v225, v212 offset:140
	ds_read_b32 v249, v212 offset:204
	s_waitcnt vmcnt(15) lgkmcnt(1)
	s_setprio 1
	v_mfma_f32_16x16x32_bf16 v[222:225], v[24:27], v[214:217], v[222:225]
	s_waitcnt vmcnt(13) lgkmcnt(0)
	v_mfma_f32_16x16x32_bf16 v[214:217], v[28:31], v[214:217], v[246:249]
	v_mfma_f32_16x16x32_bf16 v[222:225], v[16:19], v[218:221], v[222:225]
	s_waitcnt vmcnt(12)
	v_mfma_f32_16x16x32_bf16 v[216:219], v[20:23], v[218:221], v[214:217]
	s_nop 5
	s_setprio 0
	v_cndmask_b32_e64 v222, v242, v222, s[42:43]
	v_cndmask_b32_e64 v223, v242, v223, s[46:47]
	v_cndmask_b32_e64 v224, v242, v224, s[48:49]
	v_cndmask_b32_e64 v225, v242, v225, s[50:51]
	v_cndmask_b32_e64 v216, v242, v216, s[44:45]
	v_cndmask_b32_e64 v217, v242, v217, s[52:53]
	v_cndmask_b32_e64 v218, v242, v218, s[54:55]
	v_cndmask_b32_e64 v219, v242, v219, s[56:57]
	v_max3_f32 v215, v222, v223, v224
	v_max3_f32 v213, v225, v216, v217
	v_max3_f32 v215, v215, v218, v219
	v_max_f32_e32 v215, v215, v213
	v_add_f32_e32 v214, 0x41000000, v170
	v_cmp_gt_f32_e32 vcc, v215, v214
	s_cbranch_vccz .LBB0_351
	v_mov_b32_e32 v214, v215
	s_nop 1
	v_permlane16_swap_b32 v215, v214
	s_nop 0
	v_max_f32_e32 v214, v214, v214
	v_max_f32_e32 v215, v215, v215
	v_max_f32_e32 v215, v215, v214
	v_mov_b32_e32 v214, v215
	s_nop 1
	v_permlane32_swap_b32 v214, v215
	s_nop 0
	v_max3_f32 v215, v170, v214, v215
	v_sub_f32_e32 v170, v170, v215
	v_exp_f32_e32 v170, v170
	s_nop 0
	v_pk_mul_f32 v[74:75], v[74:75], v[170:171] op_sel_hi:[1,0]
	v_pk_mul_f32 v[72:73], v[72:73], v[170:171] op_sel_hi:[1,0]
	v_pk_mul_f32 v[70:71], v[70:71], v[170:171] op_sel_hi:[1,0]
	v_pk_mul_f32 v[68:69], v[68:69], v[170:171] op_sel_hi:[1,0]
	v_pk_mul_f32 v[66:67], v[66:67], v[170:171] op_sel_hi:[1,0]
	v_pk_mul_f32 v[64:65], v[64:65], v[170:171] op_sel_hi:[1,0]
	v_pk_mul_f32 v[62:63], v[62:63], v[170:171] op_sel_hi:[1,0]
	v_pk_mul_f32 v[60:61], v[60:61], v[170:171] op_sel_hi:[1,0]
	v_pk_mul_f32 v[78:79], v[78:79], v[170:171] op_sel_hi:[1,0]
	v_pk_mul_f32 v[76:77], v[76:77], v[170:171] op_sel_hi:[1,0]
	v_mov_b32_e32 v170, v215
.LBB0_351:
	v_pk_add_f32 v[222:223], v[222:223], v[170:171] op_sel_hi:[1,0] neg_lo:[0,1] neg_hi:[0,1]
	v_pk_add_f32 v[224:225], v[224:225], v[170:171] op_sel_hi:[1,0] neg_lo:[0,1] neg_hi:[0,1]
	v_pk_add_f32 v[216:217], v[216:217], v[170:171] op_sel_hi:[1,0] neg_lo:[0,1] neg_hi:[0,1]
	v_pk_add_f32 v[218:219], v[218:219], v[170:171] op_sel_hi:[1,0] neg_lo:[0,1] neg_hi:[0,1]
	v_exp_f32_e32 v222, v222
	v_exp_f32_e32 v223, v223
	v_exp_f32_e32 v224, v224
	v_exp_f32_e32 v225, v225
	v_exp_f32_e32 v216, v216
	v_exp_f32_e32 v217, v217
	v_exp_f32_e32 v218, v218
	v_exp_f32_e32 v219, v219
	v_mov_b32_e32 v37, v36
	v_mov_b32_e32 v38, v36
	v_mov_b32_e32 v39, v36
	v_cvt_pk_bf16_f32 v214, v222, v223
	v_cvt_pk_bf16_f32 v215, v224, v225
	v_cvt_pk_bf16_f32 v216, v216, v217
	v_cvt_pk_bf16_f32 v217, v218, v219
	s_waitcnt vmcnt(11)
	s_nop 0
	s_setprio 1
	v_mfma_f32_16x16x32_bf16 v[72:75], v[0:3], v[214:217], v[72:75]
	s_waitcnt vmcnt(10)
	v_mfma_f32_16x16x32_bf16 v[68:71], v[4:7], v[214:217], v[68:71]
	s_waitcnt vmcnt(9)
	v_mfma_f32_16x16x32_bf16 v[64:67], v[8:11], v[214:217], v[64:67]
	s_waitcnt vmcnt(8)
	v_mfma_f32_16x16x32_bf16 v[60:63], v[12:15], v[214:217], v[60:63]
	v_mfma_f32_16x16x32_bf16 v[76:79], v[36:39], v[214:217], v[76:79]
	s_setprio 0
	ds_read_b128 v[214:217], v168 offset:22528
	ds_read_b128 v[218:221], v168 offset:23552
	ds_read_b32 v222, v212 offset:64
	ds_read_b32 v246, v212 offset:128
	ds_read_b32 v223, v212 offset:68
	ds_read_b32 v247, v212 offset:132
	ds_read_b32 v224, v212 offset:72
	ds_read_b32 v248, v212 offset:136
	ds_read_b32 v225, v212 offset:76
	ds_read_b32 v249, v212 offset:140
	s_waitcnt lgkmcnt(1)
	s_setprio 1
	v_mfma_f32_16x16x32_bf16 v[222:225], v[24:27], v[214:217], v[222:225]
	s_waitcnt lgkmcnt(0)
	v_mfma_f32_16x16x32_bf16 v[214:217], v[28:31], v[214:217], v[246:249]
	v_mfma_f32_16x16x32_bf16 v[214:217], v[20:23], v[218:221], v[214:217]
	v_mfma_f32_16x16x32_bf16 v[222:225], v[16:19], v[218:221], v[222:225]
	s_nop 5
	s_nop 0
	s_setprio 0
	v_bfi_b32 v214, v173, v214, s29
	v_bfi_b32 v215, v174, v215, s29
	v_bfi_b32 v222, v156, v222, s29
	v_bfi_b32 v223, v157, v223, s29
	v_bfi_b32 v216, v175, v216, s29
	v_bfi_b32 v224, v158, v224, s29
	v_bfi_b32 v225, v159, v225, s29
	v_bfi_b32 v217, v176, v217, s29
	v_max3_f32 v218, v214, v215, v222
	v_max3_f32 v220, v223, v216, v224
	v_max3_f32 v218, v218, v225, v217
	v_max_f32_e32 v218, v218, v220
	v_add_f32_e32 v219, 0x41000000, v172
	v_cmp_gt_f32_e32 vcc, v218, v219
	s_cbranch_vccz .LBB0_353
	v_mov_b32_e32 v219, v218
	s_nop 1
	v_permlane16_swap_b32 v218, v219
	s_nop 0
	v_max_f32_e32 v219, v219, v219
	v_max_f32_e32 v218, v218, v218
	v_max_f32_e32 v218, v218, v219
	v_mov_b32_e32 v219, v218
	s_nop 1
	v_permlane32_swap_b32 v218, v219
	s_nop 0
	v_max3_f32 v218, v172, v218, v219
	v_sub_f32_e32 v172, v172, v218
	v_exp_f32_e32 v172, v172
	s_nop 0
	v_pk_mul_f32 v[114:115], v[114:115], v[172:173] op_sel_hi:[1,0]
	v_pk_mul_f32 v[112:113], v[112:113], v[172:173] op_sel_hi:[1,0]
	v_pk_mul_f32 v[110:111], v[110:111], v[172:173] op_sel_hi:[1,0]
	v_pk_mul_f32 v[108:109], v[108:109], v[172:173] op_sel_hi:[1,0]
	v_pk_mul_f32 v[106:107], v[106:107], v[172:173] op_sel_hi:[1,0]
	v_pk_mul_f32 v[104:105], v[104:105], v[172:173] op_sel_hi:[1,0]
	v_pk_mul_f32 v[102:103], v[102:103], v[172:173] op_sel_hi:[1,0]
	v_pk_mul_f32 v[100:101], v[100:101], v[172:173] op_sel_hi:[1,0]
	v_pk_mul_f32 v[118:119], v[118:119], v[172:173] op_sel_hi:[1,0]
	v_pk_mul_f32 v[116:117], v[116:117], v[172:173] op_sel_hi:[1,0]
	v_mov_b32_e32 v172, v218
.LBB0_353:
	v_pk_add_f32 v[216:217], v[216:217], v[172:173] op_sel_hi:[1,0] neg_lo:[0,1] neg_hi:[0,1]
	v_pk_add_f32 v[214:215], v[214:215], v[172:173] op_sel_hi:[1,0] neg_lo:[0,1] neg_hi:[0,1]
	v_pk_add_f32 v[222:223], v[222:223], v[172:173] op_sel_hi:[1,0] neg_lo:[0,1] neg_hi:[0,1]
	v_pk_add_f32 v[224:225], v[224:225], v[172:173] op_sel_hi:[1,0] neg_lo:[0,1] neg_hi:[0,1]
	v_exp_f32_e32 v216, v216
	v_exp_f32_e32 v217, v217
	v_exp_f32_e32 v214, v214
	v_exp_f32_e32 v215, v215
	v_exp_f32_e32 v222, v222
	v_exp_f32_e32 v223, v223
	v_exp_f32_e32 v224, v224
	v_exp_f32_e32 v225, v225
	v_cvt_pk_bf16_f32 v217, v216, v217
	v_cvt_pk_bf16_f32 v216, v214, v215
	v_cvt_pk_bf16_f32 v214, v222, v223
	v_cvt_pk_bf16_f32 v215, v224, v225
	s_nop 1
	s_setprio 1
	v_mfma_f32_16x16x32_bf16 v[112:115], v[0:3], v[214:217], v[112:115]
	v_mfma_f32_16x16x32_bf16 v[108:111], v[4:7], v[214:217], v[108:111]
	v_mfma_f32_16x16x32_bf16 v[104:107], v[8:11], v[214:217], v[104:107]
	v_mfma_f32_16x16x32_bf16 v[100:103], v[12:15], v[214:217], v[100:103]
	v_mfma_f32_16x16x32_bf16 v[116:119], v[36:39], v[214:217], v[116:119]
	s_setprio 0
	ds_read_b128 v[214:217], v168 offset:24576
	ds_read_b128 v[218:221], v168 offset:25600
	ds_read_b32 v222, v212
	ds_read_b32 v246, v212 offset:64
	ds_read_b32 v223, v212 offset:4
	ds_read_b32 v247, v212 offset:68
	ds_read_b32 v224, v212 offset:8
	ds_read_b32 v248, v212 offset:72
	ds_read_b32 v225, v212 offset:12
	ds_read_b32 v249, v212 offset:76
	s_waitcnt lgkmcnt(1)
	s_setprio 1
	v_mfma_f32_16x16x32_bf16 v[24:27], v[24:27], v[214:217], v[222:225]
	v_mfma_f32_16x16x32_bf16 v[16:19], v[16:19], v[218:221], v[24:27]
	s_waitcnt lgkmcnt(0)
	s_nop 5
	v_mfma_f32_16x16x32_bf16 v[24:27], v[28:31], v[214:217], v[246:249]
	v_mfma_f32_16x16x32_bf16 v[20:23], v[20:23], v[218:221], v[24:27]
	s_nop 4
	s_setprio 0
	v_cndmask_b32_e64 v16, v242, v16, s[58:59]
	s_nop 0
	v_bfi_b32 v17, v177, v17, s29
	v_bfi_b32 v18, v178, v18, s29
	v_bfi_b32 v19, v183, v19, s29
	v_bfi_b32 v20, v184, v20, s29
	v_bfi_b32 v21, v185, v21, s29
	v_bfi_b32 v22, v186, v22, s29
	v_bfi_b32 v23, v187, v23, s29
	v_max3_f32 v24, v16, v17, v18
	v_max3_f32 v26, v19, v20, v21
	v_max3_f32 v24, v24, v22, v23
	v_max_f32_e32 v24, v24, v26
	v_add_f32_e32 v25, 0x41000000, v171
	v_cmp_gt_f32_e32 vcc, v24, v25
	s_cbranch_vccz .LBB0_355
	v_mov_b32_e32 v25, v24
	s_nop 1
	v_permlane16_swap_b32 v24, v25
	s_nop 0
	v_max_f32_e32 v25, v25, v25
	v_max_f32_e32 v24, v24, v24
	v_max_f32_e32 v24, v24, v25
	v_mov_b32_e32 v25, v24
	s_nop 1
	v_permlane32_swap_b32 v24, v25
	s_nop 0
	v_max3_f32 v25, v171, v24, v25
	v_sub_f32_e32 v24, v171, v25
	v_exp_f32_e32 v24, v24
	v_mov_b32_e32 v171, v25
	v_pk_mul_f32 v[94:95], v[94:95], v[24:25] op_sel_hi:[1,0]
	v_pk_mul_f32 v[92:93], v[92:93], v[24:25] op_sel_hi:[1,0]
	v_pk_mul_f32 v[90:91], v[90:91], v[24:25] op_sel_hi:[1,0]
	v_pk_mul_f32 v[88:89], v[88:89], v[24:25] op_sel_hi:[1,0]
	v_pk_mul_f32 v[86:87], v[86:87], v[24:25] op_sel_hi:[1,0]
	v_pk_mul_f32 v[84:85], v[84:85], v[24:25] op_sel_hi:[1,0]
	v_pk_mul_f32 v[82:83], v[82:83], v[24:25] op_sel_hi:[1,0]
	v_pk_mul_f32 v[80:81], v[80:81], v[24:25] op_sel_hi:[1,0]
	v_pk_mul_f32 v[98:99], v[98:99], v[24:25] op_sel_hi:[1,0]
	v_pk_mul_f32 v[96:97], v[96:97], v[24:25] op_sel_hi:[1,0]
.LBB0_355:
	v_pk_add_f32 v[16:17], v[16:17], v[170:171] op_sel:[0,1] op_sel_hi:[1,1] neg_lo:[0,1] neg_hi:[0,1]
	v_pk_add_f32 v[18:19], v[18:19], v[170:171] op_sel:[0,1] op_sel_hi:[1,1] neg_lo:[0,1] neg_hi:[0,1]
	v_pk_add_f32 v[20:21], v[20:21], v[170:171] op_sel:[0,1] op_sel_hi:[1,1] neg_lo:[0,1] neg_hi:[0,1]
	v_pk_add_f32 v[22:23], v[22:23], v[170:171] op_sel:[0,1] op_sel_hi:[1,1] neg_lo:[0,1] neg_hi:[0,1]
	v_exp_f32_e32 v16, v16
	v_exp_f32_e32 v17, v17
	v_exp_f32_e32 v18, v18
	v_exp_f32_e32 v19, v19
	v_exp_f32_e32 v20, v20
	v_exp_f32_e32 v21, v21
	v_exp_f32_e32 v22, v22
	v_exp_f32_e32 v23, v23
	v_cvt_pk_bf16_f32 v16, v16, v17
	v_cvt_pk_bf16_f32 v17, v18, v19
	v_cvt_pk_bf16_f32 v18, v20, v21
	v_cvt_pk_bf16_f32 v19, v22, v23
	s_nop 1
	s_setprio 1
	v_mfma_f32_16x16x32_bf16 v[92:95], v[0:3], v[16:19], v[92:95]
	v_mfma_f32_16x16x32_bf16 v[88:91], v[4:7], v[16:19], v[88:91]
	v_mfma_f32_16x16x32_bf16 v[84:87], v[8:11], v[16:19], v[84:87]
	v_mfma_f32_16x16x32_bf16 v[80:83], v[12:15], v[16:19], v[80:83]
	v_mfma_f32_16x16x32_bf16 v[96:99], v[36:39], v[16:19], v[96:99]
	s_setprio 0
	s_cmp_eq_u32 s34, 0x70000
	s_cselect_b32 s40, s60, s30
	s_lshl_b32 s0, s40, 1
	s_lshl_b64 s[60:61], s[0:1], 14
	v_lshl_add_u64 v[0:1], v[164:165], 0, s[60:61]
	s_mov_b32 s41, s1
	s_lshl_b64 s[40:41], s[40:41], 15
	global_load_dwordx4 v[24:27], v[0:1], off
	global_load_dwordx4 v[16:19], v[0:1], off offset:1024
	v_add_co_u32_e32 v0, vcc, s72, v0
	v_lshl_add_u64 v[12:13], v[166:167], 0, s[40:41]
	s_nop 0
	v_addc_co_u32_e32 v1, vcc, 0, v1, vcc
	global_load_dwordx4 v[28:31], v[0:1], off
	global_load_dwordx4 v[20:23], v[0:1], off offset:1024
	s_nop 0
	global_load_dwordx4 v[0:3], v[12:13], off
	global_load_dwordx4 v[4:7], v[12:13], off offset:1024
	global_load_dwordx4 v[8:11], v[12:13], off offset:2048
	s_nop 0
	global_load_dwordx4 v[12:15], v[12:13], off offset:3072
	ds_read_b128 v[214:217], v168 offset:22528
	ds_read_b128 v[218:221], v168 offset:23552
	ds_read_b32 v222, v212 offset:192
	ds_read_b32 v246, v212 offset:256
	ds_read_b32 v223, v212 offset:196
	ds_read_b32 v247, v212 offset:260
	ds_read_b32 v224, v212 offset:200
	ds_read_b32 v248, v212 offset:264
	ds_read_b32 v225, v212 offset:204
	ds_read_b32 v249, v212 offset:268
	s_waitcnt vmcnt(15) lgkmcnt(1)
	s_setprio 1
	v_mfma_f32_16x16x32_bf16 v[222:225], v[136:139], v[214:217], v[222:225]
	s_waitcnt vmcnt(13) lgkmcnt(0)
	v_mfma_f32_16x16x32_bf16 v[214:217], v[148:151], v[214:217], v[246:249]
	s_waitcnt vmcnt(12)
	v_mfma_f32_16x16x32_bf16 v[214:217], v[144:147], v[218:221], v[214:217]
	v_mfma_f32_16x16x32_bf16 v[222:225], v[140:143], v[218:221], v[222:225]
	s_nop 5
	s_nop 0
	s_setprio 0
	v_bfi_b32 v214, v192, v214, s29
	v_bfi_b32 v215, v193, v215, s29
	v_bfi_b32 v222, v188, v222, s29
	v_bfi_b32 v223, v189, v223, s29
	v_bfi_b32 v216, v194, v216, s29
	v_bfi_b32 v224, v190, v224, s29
	v_bfi_b32 v225, v191, v225, s29
	v_bfi_b32 v217, v195, v217, s29
	v_max3_f32 v218, v214, v215, v222
	v_max3_f32 v220, v223, v216, v224
	v_max3_f32 v218, v218, v225, v217
	v_max_f32_e32 v218, v218, v220
	v_add_f32_e32 v219, 0x41000000, v172
	v_cmp_gt_f32_e32 vcc, v218, v219
	s_cbranch_vccz .LBB0_357
	v_mov_b32_e32 v219, v218
	s_nop 1
	v_permlane16_swap_b32 v218, v219
	s_nop 0
	v_max_f32_e32 v219, v219, v219
	v_max_f32_e32 v218, v218, v218
	v_max_f32_e32 v218, v218, v219
	v_mov_b32_e32 v219, v218
	s_nop 1
	v_permlane32_swap_b32 v219, v218
	s_nop 0
	v_max3_f32 v218, v172, v219, v218
	v_sub_f32_e32 v172, v172, v218
	v_exp_f32_e32 v172, v172
	s_nop 0
	v_pk_mul_f32 v[114:115], v[114:115], v[172:173] op_sel_hi:[1,0]
	v_pk_mul_f32 v[112:113], v[112:113], v[172:173] op_sel_hi:[1,0]
	v_pk_mul_f32 v[110:111], v[110:111], v[172:173] op_sel_hi:[1,0]
	v_pk_mul_f32 v[108:109], v[108:109], v[172:173] op_sel_hi:[1,0]
	v_pk_mul_f32 v[106:107], v[106:107], v[172:173] op_sel_hi:[1,0]
	v_pk_mul_f32 v[104:105], v[104:105], v[172:173] op_sel_hi:[1,0]
	v_pk_mul_f32 v[102:103], v[102:103], v[172:173] op_sel_hi:[1,0]
	v_pk_mul_f32 v[100:101], v[100:101], v[172:173] op_sel_hi:[1,0]
	v_pk_mul_f32 v[118:119], v[118:119], v[172:173] op_sel_hi:[1,0]
	v_pk_mul_f32 v[116:117], v[116:117], v[172:173] op_sel_hi:[1,0]
	v_mov_b32_e32 v172, v218
.LBB0_357:
	v_pk_add_f32 v[216:217], v[216:217], v[172:173] op_sel_hi:[1,0] neg_lo:[0,1] neg_hi:[0,1]
	v_pk_add_f32 v[214:215], v[214:215], v[172:173] op_sel_hi:[1,0] neg_lo:[0,1] neg_hi:[0,1]
	v_pk_add_f32 v[222:223], v[222:223], v[172:173] op_sel_hi:[1,0] neg_lo:[0,1] neg_hi:[0,1]
	v_pk_add_f32 v[224:225], v[224:225], v[172:173] op_sel_hi:[1,0] neg_lo:[0,1] neg_hi:[0,1]
	v_exp_f32_e32 v216, v216
	v_exp_f32_e32 v217, v217
	v_exp_f32_e32 v214, v214
	v_exp_f32_e32 v215, v215
	v_exp_f32_e32 v222, v222
	v_exp_f32_e32 v223, v223
	v_exp_f32_e32 v224, v224
	v_exp_f32_e32 v225, v225
	v_cvt_pk_bf16_f32 v217, v216, v217
	v_cvt_pk_bf16_f32 v216, v214, v215
	v_cvt_pk_bf16_f32 v214, v222, v223
	v_cvt_pk_bf16_f32 v215, v224, v225
	s_waitcnt vmcnt(11)
	s_nop 0
	s_setprio 1
	v_mfma_f32_16x16x32_bf16 v[112:115], v[120:123], v[214:217], v[112:115]
	s_waitcnt vmcnt(10)
	v_mfma_f32_16x16x32_bf16 v[108:111], v[124:127], v[214:217], v[108:111]
	s_waitcnt vmcnt(9)
	v_mfma_f32_16x16x32_bf16 v[104:107], v[128:131], v[214:217], v[104:107]
	s_waitcnt vmcnt(8)
	v_mfma_f32_16x16x32_bf16 v[100:103], v[132:135], v[214:217], v[100:103]
	v_mfma_f32_16x16x32_bf16 v[116:119], v[36:39], v[214:217], v[116:119]
	s_setprio 0
	ds_read_b128 v[214:217], v168 offset:24576
	ds_read_b128 v[218:221], v168 offset:25600
	ds_read_b32 v222, v212 offset:128
	ds_read_b32 v246, v212 offset:192
	ds_read_b32 v223, v212 offset:132
	ds_read_b32 v247, v212 offset:196
	ds_read_b32 v224, v212 offset:136
	ds_read_b32 v248, v212 offset:200
	ds_read_b32 v225, v212 offset:140
	ds_read_b32 v249, v212 offset:204
	s_waitcnt lgkmcnt(1)
	s_setprio 1
	v_mfma_f32_16x16x32_bf16 v[222:225], v[136:139], v[214:217], v[222:225]
	s_waitcnt lgkmcnt(0)
	v_mfma_f32_16x16x32_bf16 v[214:217], v[148:151], v[214:217], v[246:249]
	s_setprio 0
	v_readlane_b32 s60, v252, 47
	s_setprio 1
	v_mfma_f32_16x16x32_bf16 v[222:225], v[140:143], v[218:221], v[222:225]
	v_mfma_f32_16x16x32_bf16 v[214:217], v[144:147], v[218:221], v[214:217]
	s_nop 6
	s_setprio 0
	v_bfi_b32 v222, v196, v222, s29
	v_bfi_b32 v223, v197, v223, s29
	v_bfi_b32 v224, v198, v224, s29
	v_bfi_b32 v225, v199, v225, s29
	v_bfi_b32 v214, v200, v214, s29
	v_bfi_b32 v215, v201, v215, s29
	v_bfi_b32 v216, v202, v216, s29
	v_bfi_b32 v217, v203, v217, s29
	v_max3_f32 v32, v222, v223, v224
	v_max3_f32 v35, v225, v214, v215
	v_max3_f32 v32, v32, v216, v217
	v_max_f32_e32 v32, v32, v35
	v_add_f32_e32 v34, 0x41000000, v171
	v_cmp_gt_f32_e32 vcc, v32, v34
	s_cbranch_vccz .LBB0_359
	v_mov_b32_e32 v34, v32
	s_nop 1
	v_permlane16_swap_b32 v32, v34
	s_nop 0
	v_max_f32_e32 v34, v34, v34
	v_max_f32_e32 v32, v32, v32
	v_max_f32_e32 v32, v32, v34
	v_mov_b32_e32 v34, v32
	s_nop 1
	v_permlane32_swap_b32 v32, v34
	s_nop 0
	v_max3_f32 v32, v171, v32, v34
	v_sub_f32_e32 v171, v171, v32
	v_exp_f32_e32 v34, v171
	v_mov_b32_e32 v171, v32
	v_pk_mul_f32 v[94:95], v[94:95], v[34:35] op_sel_hi:[1,0]
	v_pk_mul_f32 v[92:93], v[92:93], v[34:35] op_sel_hi:[1,0]
	v_pk_mul_f32 v[90:91], v[90:91], v[34:35] op_sel_hi:[1,0]
	v_pk_mul_f32 v[88:89], v[88:89], v[34:35] op_sel_hi:[1,0]
	v_pk_mul_f32 v[86:87], v[86:87], v[34:35] op_sel_hi:[1,0]
	v_pk_mul_f32 v[84:85], v[84:85], v[34:35] op_sel_hi:[1,0]
	v_pk_mul_f32 v[82:83], v[82:83], v[34:35] op_sel_hi:[1,0]
	v_pk_mul_f32 v[80:81], v[80:81], v[34:35] op_sel_hi:[1,0]
	v_pk_mul_f32 v[98:99], v[98:99], v[34:35] op_sel_hi:[1,0]
	v_pk_mul_f32 v[96:97], v[96:97], v[34:35] op_sel_hi:[1,0]
.LBB0_359:
	v_pk_add_f32 v[216:217], v[216:217], v[170:171] op_sel:[0,1] op_sel_hi:[1,1] neg_lo:[0,1] neg_hi:[0,1]
	v_pk_add_f32 v[214:215], v[214:215], v[170:171] op_sel:[0,1] op_sel_hi:[1,1] neg_lo:[0,1] neg_hi:[0,1]
	v_pk_add_f32 v[222:223], v[222:223], v[170:171] op_sel:[0,1] op_sel_hi:[1,1] neg_lo:[0,1] neg_hi:[0,1]
	v_pk_add_f32 v[224:225], v[224:225], v[170:171] op_sel:[0,1] op_sel_hi:[1,1] neg_lo:[0,1] neg_hi:[0,1]
	v_exp_f32_e32 v216, v216
	v_exp_f32_e32 v217, v217
	v_exp_f32_e32 v214, v214
	v_exp_f32_e32 v215, v215
	v_exp_f32_e32 v222, v222
	v_exp_f32_e32 v223, v223
	v_exp_f32_e32 v224, v224
	v_exp_f32_e32 v225, v225
	v_cvt_pk_bf16_f32 v217, v216, v217
	v_cvt_pk_bf16_f32 v216, v214, v215
	v_cvt_pk_bf16_f32 v214, v222, v223
	v_cvt_pk_bf16_f32 v215, v224, v225
	s_nop 1
	s_setprio 1
	v_mfma_f32_16x16x32_bf16 v[92:95], v[120:123], v[214:217], v[92:95]
	v_mfma_f32_16x16x32_bf16 v[88:91], v[124:127], v[214:217], v[88:91]
	v_mfma_f32_16x16x32_bf16 v[84:87], v[128:131], v[214:217], v[84:87]
	v_mfma_f32_16x16x32_bf16 v[80:83], v[132:135], v[214:217], v[80:83]
	v_mfma_f32_16x16x32_bf16 v[96:99], v[36:39], v[214:217], v[96:99]
	s_setprio 0
	ds_read_b128 v[214:217], v168 offset:26624
	ds_read_b128 v[218:221], v168 offset:27648
	ds_read_b32 v222, v212 offset:64
	ds_read_b32 v246, v212 offset:128
	ds_read_b32 v223, v212 offset:68
	ds_read_b32 v247, v212 offset:132
	ds_read_b32 v224, v212 offset:72
	ds_read_b32 v248, v212 offset:136
	ds_read_b32 v225, v212 offset:76
	ds_read_b32 v249, v212 offset:140
	s_waitcnt lgkmcnt(1)
	s_setprio 1
	v_mfma_f32_16x16x32_bf16 v[136:139], v[136:139], v[214:217], v[222:225]
	v_mfma_f32_16x16x32_bf16 v[136:139], v[140:143], v[218:221], v[136:139]
	s_waitcnt lgkmcnt(0)
	v_mfma_f32_16x16x32_bf16 v[140:143], v[148:151], v[214:217], v[246:249]
	v_mfma_f32_16x16x32_bf16 v[140:143], v[144:147], v[218:221], v[140:143]
	s_nop 4
	s_setprio 0
	v_bfi_b32 v136, v204, v136, s29
	v_bfi_b32 v137, v205, v137, s29
	v_bfi_b32 v138, v206, v138, s29
	v_bfi_b32 v139, v207, v139, s29
	v_bfi_b32 v140, v208, v140, s29
	v_bfi_b32 v141, v209, v141, s29
	v_bfi_b32 v142, v210, v142, s29
	v_bfi_b32 v143, v211, v143, s29
	v_max3_f32 v32, v136, v137, v138
	v_max3_f32 v35, v139, v140, v141
	v_max3_f32 v32, v32, v142, v143
	v_max_f32_e32 v32, v32, v35
	v_add_f32_e32 v34, 0x41000000, v169
	v_cmp_gt_f32_e32 vcc, v32, v34
	s_cbranch_vccz .LBB0_348
	v_mov_b32_e32 v34, v32
	s_nop 1
	v_permlane16_swap_b32 v32, v34
	s_nop 0
	v_max_f32_e32 v34, v34, v34
	v_max_f32_e32 v32, v32, v32
	v_max_f32_e32 v32, v32, v34
	v_mov_b32_e32 v34, v32
	s_nop 1
	v_permlane32_swap_b32 v32, v34
	s_nop 0
	v_max3_f32 v32, v169, v32, v34
	v_sub_f32_e32 v34, v169, v32
	v_exp_f32_e32 v34, v34
	v_mov_b32_e32 v169, v32
	v_pk_mul_f32 v[54:55], v[54:55], v[34:35] op_sel_hi:[1,0]
	v_pk_mul_f32 v[52:53], v[52:53], v[34:35] op_sel_hi:[1,0]
	v_pk_mul_f32 v[50:51], v[50:51], v[34:35] op_sel_hi:[1,0]
	v_pk_mul_f32 v[48:49], v[48:49], v[34:35] op_sel_hi:[1,0]
	v_pk_mul_f32 v[46:47], v[46:47], v[34:35] op_sel_hi:[1,0]
	v_pk_mul_f32 v[44:45], v[44:45], v[34:35] op_sel_hi:[1,0]
	v_pk_mul_f32 v[42:43], v[42:43], v[34:35] op_sel_hi:[1,0]
	v_pk_mul_f32 v[40:41], v[40:41], v[34:35] op_sel_hi:[1,0]
	v_pk_mul_f32 v[58:59], v[58:59], v[34:35] op_sel_hi:[1,0]
	v_pk_mul_f32 v[56:57], v[56:57], v[34:35] op_sel_hi:[1,0]
	s_branch .LBB0_348

.LBB0_362:
	v_pk_add_f32 v[138:139], v[138:139], v[168:169] op_sel:[0,1] op_sel_hi:[1,1] neg_lo:[0,1] neg_hi:[0,1]
	v_pk_add_f32 v[136:137], v[136:137], v[168:169] op_sel:[0,1] op_sel_hi:[1,1] neg_lo:[0,1] neg_hi:[0,1]
	v_pk_add_f32 v[140:141], v[140:141], v[168:169] op_sel:[0,1] op_sel_hi:[1,1] neg_lo:[0,1] neg_hi:[0,1]
	v_pk_add_f32 v[142:143], v[142:143], v[168:169] op_sel:[0,1] op_sel_hi:[1,1] neg_lo:[0,1] neg_hi:[0,1]
	v_exp_f32_e32 v138, v138
	v_exp_f32_e32 v139, v139
	v_exp_f32_e32 v136, v136
	v_exp_f32_e32 v137, v137
	v_exp_f32_e32 v140, v140
	v_exp_f32_e32 v141, v141
	v_exp_f32_e32 v142, v142
	v_exp_f32_e32 v143, v143
	v_mov_b32_e32 v37, v36
	v_mov_b32_e32 v38, v36
	v_mov_b32_e32 v39, v36
	v_cvt_pk_bf16_f32 v139, v138, v139
	v_cvt_pk_bf16_f32 v138, v136, v137
	v_cvt_pk_bf16_f32 v136, v140, v141
	v_cvt_pk_bf16_f32 v137, v142, v143
	s_nop 1
	s_setprio 1
	v_mfma_f32_16x16x32_bf16 v[52:55], v[120:123], v[136:139], v[52:55]
	v_mfma_f32_16x16x32_bf16 v[48:51], v[124:127], v[136:139], v[48:51]
	v_mfma_f32_16x16x32_bf16 v[44:47], v[128:131], v[136:139], v[44:47]
	v_mfma_f32_16x16x32_bf16 v[40:43], v[132:135], v[136:139], v[40:43]
	v_mfma_f32_16x16x32_bf16 v[56:59], v[36:39], v[136:139], v[56:59]
	s_setprio 0
	s_add_i32 s30, s30, 2
	s_add_u32 s24, s24, 0x10000
	s_addc_u32 s25, s25, 0
	s_add_u32 s26, s26, 0x10000
	s_addc_u32 s27, s27, 0
	s_cmp_lt_u32 s31, 6
	s_cbranch_scc0 .LBB0_379
.LBB0_363:
	ds_read_b128 v[128:131], v168 offset:20480
	v_lshl_add_u64 v[34:35], s[24:25], 0, v[162:163]
	s_mov_b32 s0, 0x12708000
	v_add_co_u32_e32 v120, vcc, s0, v34
	s_mov_b32 s0, 0x1270c000
	s_nop 0
	v_addc_co_u32_e32 v121, vcc, 0, v35, vcc
	global_load_dwordx4 v[144:147], v[120:121], off
	global_load_dwordx4 v[140:143], v[120:121], off offset:1024
	ds_read_b128 v[156:159], v168 offset:21504
	s_waitcnt vmcnt(9) lgkmcnt(1)
	s_setprio 1
	v_mfma_f32_16x16x32_bf16 v[120:123], v[24:27], v[128:131], 0
	s_setprio 0
	v_add_co_u32_e32 v34, vcc, s0, v34
	v_lshl_add_u64 v[38:39], s[26:27], 0, v[162:163]
	s_nop 0
	v_addc_co_u32_e32 v35, vcc, 0, v35, vcc
	s_waitcnt vmcnt(8) lgkmcnt(0)
	s_setprio 1
	v_mfma_f32_16x16x32_bf16 v[152:155], v[16:19], v[156:159], v[120:123]
	s_setprio 0
	global_load_dwordx4 v[148:151], v[34:35], off
	global_load_dwordx4 v[136:139], v[34:35], off offset:1024
	s_nop 0
	global_load_dwordx4 v[120:123], v[38:39], off offset:-2048
	global_load_dwordx4 v[124:127], v[38:39], off offset:-1024
	s_nop 2
	s_waitcnt vmcnt(11)
	s_setprio 1
	v_mfma_f32_16x16x32_bf16 v[174:177], v[28:31], v[128:131], 0
	s_setprio 0
	global_load_dwordx4 v[128:131], v[38:39], off
	global_load_dwordx4 v[132:135], v[38:39], off offset:1024
	s_waitcnt vmcnt(12)
	s_setprio 1
	v_mfma_f32_16x16x32_bf16 v[156:159], v[20:23], v[156:159], v[174:177]
	s_nop 4
	s_setprio 0
	v_max3_f32 v32, v152, v153, v154
	s_nop 1
	v_max3_f32 v35, v155, v156, v157
	v_max3_f32 v32, v32, v158, v159
	v_max_f32_e32 v32, v32, v35
	v_add_f32_e32 v34, 0x41000000, v170
	v_cmp_gt_f32_e32 vcc, v32, v34
	s_cbranch_vccz .LBB0_365
	v_mov_b32_e32 v34, v32
	s_nop 1
	v_permlane16_swap_b32 v32, v34
	s_nop 0
	v_max_f32_e32 v34, v34, v34
	v_max_f32_e32 v32, v32, v32
	v_max_f32_e32 v32, v32, v34
	v_mov_b32_e32 v34, v32
	s_nop 1
	v_permlane32_swap_b32 v32, v34
	s_nop 0
	v_max3_f32 v34, v170, v32, v34
	v_sub_f32_e32 v32, v170, v34
	v_exp_f32_e32 v32, v32
	v_mov_b32_e32 v170, v34
	v_pk_mul_f32 v[74:75], v[74:75], v[32:33] op_sel_hi:[1,0]
	v_pk_mul_f32 v[72:73], v[72:73], v[32:33] op_sel_hi:[1,0]
	v_pk_mul_f32 v[70:71], v[70:71], v[32:33] op_sel_hi:[1,0]
	v_pk_mul_f32 v[68:69], v[68:69], v[32:33] op_sel_hi:[1,0]
	v_pk_mul_f32 v[66:67], v[66:67], v[32:33] op_sel_hi:[1,0]
	v_pk_mul_f32 v[64:65], v[64:65], v[32:33] op_sel_hi:[1,0]
	v_pk_mul_f32 v[62:63], v[62:63], v[32:33] op_sel_hi:[1,0]
	v_pk_mul_f32 v[60:61], v[60:61], v[32:33] op_sel_hi:[1,0]
	v_pk_mul_f32 v[78:79], v[78:79], v[32:33] op_sel_hi:[1,0]
	v_pk_mul_f32 v[76:77], v[76:77], v[32:33] op_sel_hi:[1,0]
.LBB0_365:
	v_pk_add_f32 v[152:153], v[152:153], v[170:171] op_sel_hi:[1,0] neg_lo:[0,1] neg_hi:[0,1]
	v_pk_add_f32 v[154:155], v[154:155], v[170:171] op_sel_hi:[1,0] neg_lo:[0,1] neg_hi:[0,1]
	v_pk_add_f32 v[156:157], v[156:157], v[170:171] op_sel_hi:[1,0] neg_lo:[0,1] neg_hi:[0,1]
	v_pk_add_f32 v[158:159], v[158:159], v[170:171] op_sel_hi:[1,0] neg_lo:[0,1] neg_hi:[0,1]
	v_exp_f32_e32 v152, v152
	v_exp_f32_e32 v153, v153
	v_exp_f32_e32 v154, v154
	v_exp_f32_e32 v155, v155
	v_exp_f32_e32 v156, v156
	v_exp_f32_e32 v157, v157
	v_exp_f32_e32 v158, v158
	v_exp_f32_e32 v159, v159
	v_mov_b32_e32 v37, v36
	v_mov_b32_e32 v38, v36
	v_mov_b32_e32 v39, v36
	v_cvt_pk_bf16_f32 v152, v152, v153
	v_cvt_pk_bf16_f32 v153, v154, v155
	v_cvt_pk_bf16_f32 v154, v156, v157
	v_cvt_pk_bf16_f32 v155, v158, v159
	s_waitcnt vmcnt(11)
	s_nop 0
	s_setprio 1
	v_mfma_f32_16x16x32_bf16 v[72:75], v[0:3], v[152:155], v[72:75]
	s_waitcnt vmcnt(10)
	v_mfma_f32_16x16x32_bf16 v[68:71], v[4:7], v[152:155], v[68:71]
	s_waitcnt vmcnt(9)
	v_mfma_f32_16x16x32_bf16 v[64:67], v[8:11], v[152:155], v[64:67]
	s_waitcnt vmcnt(8)
	v_mfma_f32_16x16x32_bf16 v[60:63], v[12:15], v[152:155], v[60:63]
	v_mfma_f32_16x16x32_bf16 v[76:79], v[36:39], v[152:155], v[76:79]
	s_setprio 0
	ds_read_b128 v[152:155], v168 offset:22528
	ds_read_b128 v[174:177], v168 offset:23552
	s_waitcnt lgkmcnt(1)
	s_setprio 1
	v_mfma_f32_16x16x32_bf16 v[156:159], v[24:27], v[152:155], 0
	v_mfma_f32_16x16x32_bf16 v[152:155], v[28:31], v[152:155], 0
	s_waitcnt lgkmcnt(0)
	v_mfma_f32_16x16x32_bf16 v[156:159], v[16:19], v[174:177], v[156:159]
	v_mfma_f32_16x16x32_bf16 v[152:155], v[20:23], v[174:177], v[152:155]
	s_nop 6
	s_setprio 0
	v_max3_f32 v32, v156, v157, v158
	v_max3_f32 v35, v159, v152, v153
	v_max3_f32 v32, v32, v154, v155
	v_max_f32_e32 v32, v32, v35
	v_add_f32_e32 v34, 0x41000000, v172
	v_cmp_gt_f32_e32 vcc, v32, v34
	s_cbranch_vccz .LBB0_367
	v_mov_b32_e32 v34, v32
	s_nop 1
	v_permlane16_swap_b32 v32, v34
	s_nop 0
	v_max_f32_e32 v34, v34, v34
	v_max_f32_e32 v32, v32, v32
	v_max_f32_e32 v32, v32, v34
	v_mov_b32_e32 v34, v32
	s_nop 1
	v_permlane32_swap_b32 v32, v34
	s_nop 0
	v_max3_f32 v34, v172, v32, v34
	v_sub_f32_e32 v32, v172, v34
	v_exp_f32_e32 v32, v32
	v_mov_b32_e32 v172, v34
	v_pk_mul_f32 v[114:115], v[114:115], v[32:33] op_sel_hi:[1,0]
	v_pk_mul_f32 v[112:113], v[112:113], v[32:33] op_sel_hi:[1,0]
	v_pk_mul_f32 v[110:111], v[110:111], v[32:33] op_sel_hi:[1,0]
	v_pk_mul_f32 v[108:109], v[108:109], v[32:33] op_sel_hi:[1,0]
	v_pk_mul_f32 v[106:107], v[106:107], v[32:33] op_sel_hi:[1,0]
	v_pk_mul_f32 v[104:105], v[104:105], v[32:33] op_sel_hi:[1,0]
	v_pk_mul_f32 v[102:103], v[102:103], v[32:33] op_sel_hi:[1,0]
	v_pk_mul_f32 v[100:101], v[100:101], v[32:33] op_sel_hi:[1,0]
	v_pk_mul_f32 v[118:119], v[118:119], v[32:33] op_sel_hi:[1,0]
	v_pk_mul_f32 v[116:117], v[116:117], v[32:33] op_sel_hi:[1,0]
.LBB0_367:
	v_pk_add_f32 v[154:155], v[154:155], v[172:173] op_sel_hi:[1,0] neg_lo:[0,1] neg_hi:[0,1]
	v_pk_add_f32 v[152:153], v[152:153], v[172:173] op_sel_hi:[1,0] neg_lo:[0,1] neg_hi:[0,1]
	v_pk_add_f32 v[156:157], v[156:157], v[172:173] op_sel_hi:[1,0] neg_lo:[0,1] neg_hi:[0,1]
	v_pk_add_f32 v[158:159], v[158:159], v[172:173] op_sel_hi:[1,0] neg_lo:[0,1] neg_hi:[0,1]
	v_exp_f32_e32 v154, v154
	v_exp_f32_e32 v155, v155
	v_exp_f32_e32 v152, v152
	v_exp_f32_e32 v153, v153
	v_exp_f32_e32 v156, v156
	v_exp_f32_e32 v157, v157
	v_exp_f32_e32 v158, v158
	v_exp_f32_e32 v159, v159
	v_cvt_pk_bf16_f32 v155, v154, v155
	v_cvt_pk_bf16_f32 v154, v152, v153
	v_cvt_pk_bf16_f32 v152, v156, v157
	v_cvt_pk_bf16_f32 v153, v158, v159
	s_nop 1
	s_setprio 1
	v_mfma_f32_16x16x32_bf16 v[112:115], v[0:3], v[152:155], v[112:115]
	v_mfma_f32_16x16x32_bf16 v[108:111], v[4:7], v[152:155], v[108:111]
	v_mfma_f32_16x16x32_bf16 v[104:107], v[8:11], v[152:155], v[104:107]
	v_mfma_f32_16x16x32_bf16 v[100:103], v[12:15], v[152:155], v[100:103]
	v_mfma_f32_16x16x32_bf16 v[116:119], v[36:39], v[152:155], v[116:119]
	s_setprio 0
	ds_read_b128 v[152:155], v168 offset:24576
	ds_read_b128 v[174:177], v168 offset:25600
	s_waitcnt lgkmcnt(1)
	s_setprio 1
	v_mfma_f32_16x16x32_bf16 v[156:159], v[24:27], v[152:155], 0
	v_mfma_f32_16x16x32_bf16 v[152:155], v[28:31], v[152:155], 0
	s_waitcnt lgkmcnt(0)
	v_mfma_f32_16x16x32_bf16 v[156:159], v[16:19], v[174:177], v[156:159]
	v_mfma_f32_16x16x32_bf16 v[152:155], v[20:23], v[174:177], v[152:155]
	s_nop 6
	s_setprio 0
	v_max3_f32 v32, v156, v157, v158
	v_max3_f32 v35, v159, v152, v153
	v_max3_f32 v32, v32, v154, v155
	v_max_f32_e32 v32, v32, v35
	v_add_f32_e32 v34, 0x41000000, v171
	v_cmp_gt_f32_e32 vcc, v32, v34
	s_cbranch_vccz .LBB0_369
	v_mov_b32_e32 v34, v32
	s_nop 1
	v_permlane16_swap_b32 v32, v34
	s_nop 0
	v_max_f32_e32 v34, v34, v34
	v_max_f32_e32 v32, v32, v32
	v_max_f32_e32 v32, v32, v34
	v_mov_b32_e32 v34, v32
	s_nop 1
	v_permlane32_swap_b32 v34, v32
	s_nop 0
	v_max3_f32 v34, v171, v34, v32
	v_sub_f32_e32 v32, v171, v34
	v_exp_f32_e32 v32, v32
	v_mov_b32_e32 v171, v34
	v_pk_mul_f32 v[94:95], v[94:95], v[32:33] op_sel_hi:[1,0]
	v_pk_mul_f32 v[92:93], v[92:93], v[32:33] op_sel_hi:[1,0]
	v_pk_mul_f32 v[90:91], v[90:91], v[32:33] op_sel_hi:[1,0]
	v_pk_mul_f32 v[88:89], v[88:89], v[32:33] op_sel_hi:[1,0]
	v_pk_mul_f32 v[86:87], v[86:87], v[32:33] op_sel_hi:[1,0]
	v_pk_mul_f32 v[84:85], v[84:85], v[32:33] op_sel_hi:[1,0]
	v_pk_mul_f32 v[82:83], v[82:83], v[32:33] op_sel_hi:[1,0]
	v_pk_mul_f32 v[80:81], v[80:81], v[32:33] op_sel_hi:[1,0]
	v_pk_mul_f32 v[98:99], v[98:99], v[32:33] op_sel_hi:[1,0]
	v_pk_mul_f32 v[96:97], v[96:97], v[32:33] op_sel_hi:[1,0]
.LBB0_369:
	v_pk_add_f32 v[154:155], v[154:155], v[170:171] op_sel:[0,1] op_sel_hi:[1,1] neg_lo:[0,1] neg_hi:[0,1]
	v_pk_add_f32 v[152:153], v[152:153], v[170:171] op_sel:[0,1] op_sel_hi:[1,1] neg_lo:[0,1] neg_hi:[0,1]
	v_pk_add_f32 v[156:157], v[156:157], v[170:171] op_sel:[0,1] op_sel_hi:[1,1] neg_lo:[0,1] neg_hi:[0,1]
	v_pk_add_f32 v[158:159], v[158:159], v[170:171] op_sel:[0,1] op_sel_hi:[1,1] neg_lo:[0,1] neg_hi:[0,1]
	v_exp_f32_e32 v154, v154
	v_exp_f32_e32 v155, v155
	v_exp_f32_e32 v152, v152
	v_exp_f32_e32 v153, v153
	v_exp_f32_e32 v156, v156
	v_exp_f32_e32 v157, v157
	v_exp_f32_e32 v158, v158
	v_exp_f32_e32 v159, v159
	v_cvt_pk_bf16_f32 v155, v154, v155
	v_cvt_pk_bf16_f32 v154, v152, v153
	v_cvt_pk_bf16_f32 v152, v156, v157
	v_cvt_pk_bf16_f32 v153, v158, v159
	s_nop 1
	s_setprio 1
	v_mfma_f32_16x16x32_bf16 v[92:95], v[0:3], v[152:155], v[92:95]
	v_mfma_f32_16x16x32_bf16 v[88:91], v[4:7], v[152:155], v[88:91]
	v_mfma_f32_16x16x32_bf16 v[84:87], v[8:11], v[152:155], v[84:87]
	v_mfma_f32_16x16x32_bf16 v[80:83], v[12:15], v[152:155], v[80:83]
	v_mfma_f32_16x16x32_bf16 v[96:99], v[36:39], v[152:155], v[96:99]
	s_setprio 0
	ds_read_b128 v[152:155], v168 offset:26624
	s_waitcnt lgkmcnt(0)
	s_setprio 1
	v_mfma_f32_16x16x32_bf16 v[24:27], v[24:27], v[152:155], 0
	v_mfma_f32_16x16x32_bf16 v[28:31], v[28:31], v[152:155], 0
	s_setprio 0
	ds_read_b128 v[152:155], v168 offset:27648
	s_waitcnt lgkmcnt(0)
	s_setprio 1
	v_mfma_f32_16x16x32_bf16 v[16:19], v[16:19], v[152:155], v[24:27]
	v_mfma_f32_16x16x32_bf16 v[20:23], v[20:23], v[152:155], v[28:31]
	s_nop 6
	s_setprio 0
	v_max3_f32 v24, v16, v17, v18
	v_max3_f32 v26, v19, v20, v21
	v_max3_f32 v24, v24, v22, v23
	v_max_f32_e32 v24, v24, v26
	v_add_f32_e32 v25, 0x41000000, v169
	v_cmp_gt_f32_e32 vcc, v24, v25
	s_cbranch_vccz .LBB0_371
	v_mov_b32_e32 v25, v24
	s_nop 1
	v_permlane16_swap_b32 v24, v25
	s_nop 0
	v_max_f32_e32 v25, v25, v25
	v_max_f32_e32 v24, v24, v24
	v_max_f32_e32 v24, v24, v25
	v_mov_b32_e32 v25, v24
	s_nop 1
	v_permlane32_swap_b32 v24, v25
	s_nop 0
	v_max3_f32 v25, v169, v24, v25
	v_sub_f32_e32 v24, v169, v25
	v_exp_f32_e32 v24, v24
	v_mov_b32_e32 v169, v25
	v_pk_mul_f32 v[54:55], v[54:55], v[24:25] op_sel_hi:[1,0]
	v_pk_mul_f32 v[52:53], v[52:53], v[24:25] op_sel_hi:[1,0]
	v_pk_mul_f32 v[50:51], v[50:51], v[24:25] op_sel_hi:[1,0]
	v_pk_mul_f32 v[48:49], v[48:49], v[24:25] op_sel_hi:[1,0]
	v_pk_mul_f32 v[46:47], v[46:47], v[24:25] op_sel_hi:[1,0]
	v_pk_mul_f32 v[44:45], v[44:45], v[24:25] op_sel_hi:[1,0]
	v_pk_mul_f32 v[42:43], v[42:43], v[24:25] op_sel_hi:[1,0]
	v_pk_mul_f32 v[40:41], v[40:41], v[24:25] op_sel_hi:[1,0]
	v_pk_mul_f32 v[58:59], v[58:59], v[24:25] op_sel_hi:[1,0]
	v_pk_mul_f32 v[56:57], v[56:57], v[24:25] op_sel_hi:[1,0]
.LBB0_371:
	v_pk_add_f32 v[16:17], v[16:17], v[168:169] op_sel:[0,1] op_sel_hi:[1,1] neg_lo:[0,1] neg_hi:[0,1]
	v_pk_add_f32 v[18:19], v[18:19], v[168:169] op_sel:[0,1] op_sel_hi:[1,1] neg_lo:[0,1] neg_hi:[0,1]
	v_pk_add_f32 v[20:21], v[20:21], v[168:169] op_sel:[0,1] op_sel_hi:[1,1] neg_lo:[0,1] neg_hi:[0,1]
	v_pk_add_f32 v[22:23], v[22:23], v[168:169] op_sel:[0,1] op_sel_hi:[1,1] neg_lo:[0,1] neg_hi:[0,1]
	v_exp_f32_e32 v16, v16
	v_exp_f32_e32 v17, v17
	v_exp_f32_e32 v18, v18
	v_exp_f32_e32 v19, v19
	v_exp_f32_e32 v20, v20
	v_exp_f32_e32 v21, v21
	v_exp_f32_e32 v22, v22
	v_exp_f32_e32 v23, v23
	v_cvt_pk_bf16_f32 v16, v16, v17
	v_cvt_pk_bf16_f32 v17, v18, v19
	v_cvt_pk_bf16_f32 v18, v20, v21
	v_cvt_pk_bf16_f32 v19, v22, v23
	s_add_i32 s31, s30, -2
	s_nop 0
	s_setprio 1
	v_mfma_f32_16x16x32_bf16 v[52:55], v[0:3], v[16:19], v[52:55]
	v_mfma_f32_16x16x32_bf16 v[48:51], v[4:7], v[16:19], v[48:51]
	v_mfma_f32_16x16x32_bf16 v[44:47], v[8:11], v[16:19], v[44:47]
	v_mfma_f32_16x16x32_bf16 v[40:43], v[12:15], v[16:19], v[40:43]
	v_mfma_f32_16x16x32_bf16 v[56:59], v[36:39], v[16:19], v[56:59]
	s_setprio 0
	s_cmp_lt_u32 s31, 6
	s_cselect_b32 s0, s30, 0
	s_add_i32 s34, s0, s60
	ds_read_b128 v[8:11], v168 offset:20480
	s_lshl_b32 s0, s34, 1
	s_lshl_b64 s[40:41], s[0:1], 14
	v_lshl_add_u64 v[4:5], v[164:165], 0, s[40:41]
	global_load_dwordx4 v[24:27], v[4:5], off
	global_load_dwordx4 v[16:19], v[4:5], off offset:1024
	ds_read_b128 v[156:159], v168 offset:21504
	s_waitcnt vmcnt(9) lgkmcnt(1)
	s_setprio 1
	v_mfma_f32_16x16x32_bf16 v[0:3], v[144:147], v[8:11], 0
	s_setprio 0
	s_mov_b32 s35, s1
	v_add_co_u32_e32 v4, vcc, s72, v4
	s_lshl_b64 s[34:35], s[34:35], 15
	s_nop 0
	v_addc_co_u32_e32 v5, vcc, 0, v5, vcc
	v_lshl_add_u64 v[12:13], v[166:167], 0, s[34:35]
	s_waitcnt vmcnt(8) lgkmcnt(0)
	s_setprio 1
	v_mfma_f32_16x16x32_bf16 v[152:155], v[140:143], v[156:159], v[0:3]
	s_setprio 0
	global_load_dwordx4 v[28:31], v[4:5], off
	global_load_dwordx4 v[20:23], v[4:5], off offset:1024
	s_nop 0
	global_load_dwordx4 v[0:3], v[12:13], off
	global_load_dwordx4 v[4:7], v[12:13], off offset:1024
	s_nop 2
	s_waitcnt vmcnt(11)
	s_setprio 1
	v_mfma_f32_16x16x32_bf16 v[174:177], v[148:151], v[8:11], 0
	s_setprio 0
	global_load_dwordx4 v[8:11], v[12:13], off offset:2048
	s_nop 0
	global_load_dwordx4 v[12:15], v[12:13], off offset:3072
	s_waitcnt vmcnt(12)
	s_setprio 1
	v_mfma_f32_16x16x32_bf16 v[156:159], v[136:139], v[156:159], v[174:177]
	s_nop 4
	s_setprio 0
	v_max3_f32 v32, v152, v153, v154
	s_nop 1
	v_max3_f32 v35, v155, v156, v157
	v_max3_f32 v32, v32, v158, v159
	v_max_f32_e32 v32, v32, v35
	v_add_f32_e32 v34, 0x41000000, v170
	v_cmp_gt_f32_e32 vcc, v32, v34
	s_cbranch_vccz .LBB0_373
	v_mov_b32_e32 v34, v32
	s_nop 1
	v_permlane16_swap_b32 v32, v34
	s_nop 0
	v_max_f32_e32 v34, v34, v34
	v_max_f32_e32 v32, v32, v32
	v_max_f32_e32 v32, v32, v34
	v_mov_b32_e32 v34, v32
	s_nop 1
	v_permlane32_swap_b32 v34, v32
	s_nop 0
	v_max3_f32 v34, v170, v34, v32
	v_sub_f32_e32 v32, v170, v34
	v_exp_f32_e32 v32, v32
	v_mov_b32_e32 v170, v34
	v_pk_mul_f32 v[74:75], v[74:75], v[32:33] op_sel_hi:[1,0]
	v_pk_mul_f32 v[72:73], v[72:73], v[32:33] op_sel_hi:[1,0]
	v_pk_mul_f32 v[70:71], v[70:71], v[32:33] op_sel_hi:[1,0]
	v_pk_mul_f32 v[68:69], v[68:69], v[32:33] op_sel_hi:[1,0]
	v_pk_mul_f32 v[66:67], v[66:67], v[32:33] op_sel_hi:[1,0]
	v_pk_mul_f32 v[64:65], v[64:65], v[32:33] op_sel_hi:[1,0]
	v_pk_mul_f32 v[62:63], v[62:63], v[32:33] op_sel_hi:[1,0]
	v_pk_mul_f32 v[60:61], v[60:61], v[32:33] op_sel_hi:[1,0]
	v_pk_mul_f32 v[78:79], v[78:79], v[32:33] op_sel_hi:[1,0]
	v_pk_mul_f32 v[76:77], v[76:77], v[32:33] op_sel_hi:[1,0]
.LBB0_373:
	v_pk_add_f32 v[152:153], v[152:153], v[170:171] op_sel_hi:[1,0] neg_lo:[0,1] neg_hi:[0,1]
	v_pk_add_f32 v[154:155], v[154:155], v[170:171] op_sel_hi:[1,0] neg_lo:[0,1] neg_hi:[0,1]
	v_pk_add_f32 v[156:157], v[156:157], v[170:171] op_sel_hi:[1,0] neg_lo:[0,1] neg_hi:[0,1]
	v_pk_add_f32 v[158:159], v[158:159], v[170:171] op_sel_hi:[1,0] neg_lo:[0,1] neg_hi:[0,1]
	v_exp_f32_e32 v152, v152
	v_exp_f32_e32 v153, v153
	v_exp_f32_e32 v154, v154
	v_exp_f32_e32 v155, v155
	v_exp_f32_e32 v156, v156
	v_exp_f32_e32 v157, v157
	v_exp_f32_e32 v158, v158
	v_exp_f32_e32 v159, v159
	v_cvt_pk_bf16_f32 v152, v152, v153
	v_cvt_pk_bf16_f32 v153, v154, v155
	v_cvt_pk_bf16_f32 v154, v156, v157
	v_cvt_pk_bf16_f32 v155, v158, v159
	s_waitcnt vmcnt(11)
	s_nop 0
	s_setprio 1
	v_mfma_f32_16x16x32_bf16 v[72:75], v[120:123], v[152:155], v[72:75]
	s_waitcnt vmcnt(10)
	v_mfma_f32_16x16x32_bf16 v[68:71], v[124:127], v[152:155], v[68:71]
	s_waitcnt vmcnt(9)
	v_mfma_f32_16x16x32_bf16 v[64:67], v[128:131], v[152:155], v[64:67]
	s_waitcnt vmcnt(8)
	v_mfma_f32_16x16x32_bf16 v[60:63], v[132:135], v[152:155], v[60:63]
	v_mfma_f32_16x16x32_bf16 v[76:79], v[36:39], v[152:155], v[76:79]
	s_setprio 0
	ds_read_b128 v[152:155], v168 offset:22528
	ds_read_b128 v[174:177], v168 offset:23552
	s_waitcnt lgkmcnt(1)
	s_setprio 1
	v_mfma_f32_16x16x32_bf16 v[156:159], v[144:147], v[152:155], 0
	v_mfma_f32_16x16x32_bf16 v[152:155], v[148:151], v[152:155], 0
	s_waitcnt lgkmcnt(0)
	v_mfma_f32_16x16x32_bf16 v[156:159], v[140:143], v[174:177], v[156:159]
	v_mfma_f32_16x16x32_bf16 v[152:155], v[136:139], v[174:177], v[152:155]
	s_nop 6
	s_setprio 0
	v_max3_f32 v32, v156, v157, v158
	v_max3_f32 v35, v159, v152, v153
	v_max3_f32 v32, v32, v154, v155
	v_max_f32_e32 v32, v32, v35
	v_add_f32_e32 v34, 0x41000000, v172
	v_cmp_gt_f32_e32 vcc, v32, v34
	s_cbranch_vccz .LBB0_375
	v_mov_b32_e32 v34, v32
	s_nop 1
	v_permlane16_swap_b32 v32, v34
	s_nop 0
	v_max_f32_e32 v34, v34, v34
	v_max_f32_e32 v32, v32, v32
	v_max_f32_e32 v32, v32, v34
	v_mov_b32_e32 v34, v32
	s_nop 1
	v_permlane32_swap_b32 v32, v34
	s_nop 0
	v_max3_f32 v34, v172, v32, v34
	v_sub_f32_e32 v32, v172, v34
	v_exp_f32_e32 v32, v32
	v_mov_b32_e32 v172, v34
	v_pk_mul_f32 v[114:115], v[114:115], v[32:33] op_sel_hi:[1,0]
	v_pk_mul_f32 v[112:113], v[112:113], v[32:33] op_sel_hi:[1,0]
	v_pk_mul_f32 v[110:111], v[110:111], v[32:33] op_sel_hi:[1,0]
	v_pk_mul_f32 v[108:109], v[108:109], v[32:33] op_sel_hi:[1,0]
	v_pk_mul_f32 v[106:107], v[106:107], v[32:33] op_sel_hi:[1,0]
	v_pk_mul_f32 v[104:105], v[104:105], v[32:33] op_sel_hi:[1,0]
	v_pk_mul_f32 v[102:103], v[102:103], v[32:33] op_sel_hi:[1,0]
	v_pk_mul_f32 v[100:101], v[100:101], v[32:33] op_sel_hi:[1,0]
	v_pk_mul_f32 v[118:119], v[118:119], v[32:33] op_sel_hi:[1,0]
	v_pk_mul_f32 v[116:117], v[116:117], v[32:33] op_sel_hi:[1,0]
.LBB0_375:
	v_pk_add_f32 v[154:155], v[154:155], v[172:173] op_sel_hi:[1,0] neg_lo:[0,1] neg_hi:[0,1]
	v_pk_add_f32 v[152:153], v[152:153], v[172:173] op_sel_hi:[1,0] neg_lo:[0,1] neg_hi:[0,1]
	v_pk_add_f32 v[156:157], v[156:157], v[172:173] op_sel_hi:[1,0] neg_lo:[0,1] neg_hi:[0,1]
	v_pk_add_f32 v[158:159], v[158:159], v[172:173] op_sel_hi:[1,0] neg_lo:[0,1] neg_hi:[0,1]
	v_exp_f32_e32 v154, v154
	v_exp_f32_e32 v155, v155
	v_exp_f32_e32 v152, v152
	v_exp_f32_e32 v153, v153
	v_exp_f32_e32 v156, v156
	v_exp_f32_e32 v157, v157
	v_exp_f32_e32 v158, v158
	v_exp_f32_e32 v159, v159
	v_cvt_pk_bf16_f32 v155, v154, v155
	v_cvt_pk_bf16_f32 v154, v152, v153
	v_cvt_pk_bf16_f32 v152, v156, v157
	v_cvt_pk_bf16_f32 v153, v158, v159
	s_nop 1
	s_setprio 1
	v_mfma_f32_16x16x32_bf16 v[112:115], v[120:123], v[152:155], v[112:115]
	v_mfma_f32_16x16x32_bf16 v[108:111], v[124:127], v[152:155], v[108:111]
	v_mfma_f32_16x16x32_bf16 v[104:107], v[128:131], v[152:155], v[104:107]
	v_mfma_f32_16x16x32_bf16 v[100:103], v[132:135], v[152:155], v[100:103]
	v_mfma_f32_16x16x32_bf16 v[116:119], v[36:39], v[152:155], v[116:119]
	s_setprio 0
	ds_read_b128 v[152:155], v168 offset:24576
	ds_read_b128 v[174:177], v168 offset:25600
	s_waitcnt lgkmcnt(1)
	s_setprio 1
	v_mfma_f32_16x16x32_bf16 v[156:159], v[144:147], v[152:155], 0
	v_mfma_f32_16x16x32_bf16 v[152:155], v[148:151], v[152:155], 0
	s_waitcnt lgkmcnt(0)
	v_mfma_f32_16x16x32_bf16 v[156:159], v[140:143], v[174:177], v[156:159]
	v_mfma_f32_16x16x32_bf16 v[152:155], v[136:139], v[174:177], v[152:155]
	s_nop 6
	s_setprio 0
	v_max3_f32 v32, v156, v157, v158
	v_max3_f32 v35, v159, v152, v153
	v_max3_f32 v32, v32, v154, v155
	v_max_f32_e32 v32, v32, v35
	v_add_f32_e32 v34, 0x41000000, v171
	v_cmp_gt_f32_e32 vcc, v32, v34
	s_cbranch_vccz .LBB0_377
	v_mov_b32_e32 v34, v32
	s_nop 1
	v_permlane16_swap_b32 v32, v34
	s_nop 0
	v_max_f32_e32 v34, v34, v34
	v_max_f32_e32 v32, v32, v32
	v_max_f32_e32 v32, v32, v34
	v_mov_b32_e32 v34, v32
	s_nop 1
	v_permlane32_swap_b32 v32, v34
	s_nop 0
	v_max3_f32 v34, v171, v32, v34
	v_sub_f32_e32 v32, v171, v34
	v_exp_f32_e32 v32, v32
	v_mov_b32_e32 v171, v34
	v_pk_mul_f32 v[94:95], v[94:95], v[32:33] op_sel_hi:[1,0]
	v_pk_mul_f32 v[92:93], v[92:93], v[32:33] op_sel_hi:[1,0]
	v_pk_mul_f32 v[90:91], v[90:91], v[32:33] op_sel_hi:[1,0]
	v_pk_mul_f32 v[88:89], v[88:89], v[32:33] op_sel_hi:[1,0]
	v_pk_mul_f32 v[86:87], v[86:87], v[32:33] op_sel_hi:[1,0]
	v_pk_mul_f32 v[84:85], v[84:85], v[32:33] op_sel_hi:[1,0]
	v_pk_mul_f32 v[82:83], v[82:83], v[32:33] op_sel_hi:[1,0]
	v_pk_mul_f32 v[80:81], v[80:81], v[32:33] op_sel_hi:[1,0]
	v_pk_mul_f32 v[98:99], v[98:99], v[32:33] op_sel_hi:[1,0]
	v_pk_mul_f32 v[96:97], v[96:97], v[32:33] op_sel_hi:[1,0]
.LBB0_377:
	v_pk_add_f32 v[154:155], v[154:155], v[170:171] op_sel:[0,1] op_sel_hi:[1,1] neg_lo:[0,1] neg_hi:[0,1]
	v_pk_add_f32 v[152:153], v[152:153], v[170:171] op_sel:[0,1] op_sel_hi:[1,1] neg_lo:[0,1] neg_hi:[0,1]
	v_pk_add_f32 v[156:157], v[156:157], v[170:171] op_sel:[0,1] op_sel_hi:[1,1] neg_lo:[0,1] neg_hi:[0,1]
	v_pk_add_f32 v[158:159], v[158:159], v[170:171] op_sel:[0,1] op_sel_hi:[1,1] neg_lo:[0,1] neg_hi:[0,1]
	v_exp_f32_e32 v154, v154
	v_exp_f32_e32 v155, v155
	v_exp_f32_e32 v152, v152
	v_exp_f32_e32 v153, v153
	v_exp_f32_e32 v156, v156
	v_exp_f32_e32 v157, v157
	v_exp_f32_e32 v158, v158
	v_exp_f32_e32 v159, v159
	v_cvt_pk_bf16_f32 v155, v154, v155
	v_cvt_pk_bf16_f32 v154, v152, v153
	v_cvt_pk_bf16_f32 v152, v156, v157
	v_cvt_pk_bf16_f32 v153, v158, v159
	s_nop 1
	s_setprio 1
	v_mfma_f32_16x16x32_bf16 v[92:95], v[120:123], v[152:155], v[92:95]
	v_mfma_f32_16x16x32_bf16 v[88:91], v[124:127], v[152:155], v[88:91]
	v_mfma_f32_16x16x32_bf16 v[84:87], v[128:131], v[152:155], v[84:87]
	v_mfma_f32_16x16x32_bf16 v[80:83], v[132:135], v[152:155], v[80:83]
	v_mfma_f32_16x16x32_bf16 v[96:99], v[36:39], v[152:155], v[96:99]
	s_setprio 0
	ds_read_b128 v[152:155], v168 offset:26624
	s_waitcnt lgkmcnt(0)
	s_setprio 1
	v_mfma_f32_16x16x32_bf16 v[144:147], v[144:147], v[152:155], 0
	v_mfma_f32_16x16x32_bf16 v[148:151], v[148:151], v[152:155], 0
	s_setprio 0
	ds_read_b128 v[152:155], v168 offset:27648
	s_waitcnt lgkmcnt(0)
	s_setprio 1
	v_mfma_f32_16x16x32_bf16 v[140:143], v[140:143], v[152:155], v[144:147]
	v_mfma_f32_16x16x32_bf16 v[136:139], v[136:139], v[152:155], v[148:151]
	s_nop 6
	s_setprio 0
	v_max3_f32 v32, v140, v141, v142
	v_max3_f32 v35, v143, v136, v137
	v_max3_f32 v32, v32, v138, v139
	v_max_f32_e32 v32, v32, v35
	v_add_f32_e32 v34, 0x41000000, v169
	v_cmp_gt_f32_e32 vcc, v32, v34
	s_cbranch_vccz .LBB0_362
	v_mov_b32_e32 v34, v32
	s_nop 1
	v_permlane16_swap_b32 v32, v34
	s_nop 0
	v_max_f32_e32 v34, v34, v34
	v_max_f32_e32 v32, v32, v32
	v_max_f32_e32 v32, v32, v34
	v_mov_b32_e32 v34, v32
	s_nop 1
	v_permlane32_swap_b32 v32, v34
	s_nop 0
	v_max3_f32 v34, v169, v32, v34
	v_sub_f32_e32 v32, v169, v34
	v_exp_f32_e32 v32, v32
	v_mov_b32_e32 v169, v34
	v_pk_mul_f32 v[54:55], v[54:55], v[32:33] op_sel_hi:[1,0]
	v_pk_mul_f32 v[52:53], v[52:53], v[32:33] op_sel_hi:[1,0]
	v_pk_mul_f32 v[50:51], v[50:51], v[32:33] op_sel_hi:[1,0]
	v_pk_mul_f32 v[48:49], v[48:49], v[32:33] op_sel_hi:[1,0]
	v_pk_mul_f32 v[46:47], v[46:47], v[32:33] op_sel_hi:[1,0]
	v_pk_mul_f32 v[44:45], v[44:45], v[32:33] op_sel_hi:[1,0]
	v_pk_mul_f32 v[42:43], v[42:43], v[32:33] op_sel_hi:[1,0]
	v_pk_mul_f32 v[40:41], v[40:41], v[32:33] op_sel_hi:[1,0]
	v_pk_mul_f32 v[58:59], v[58:59], v[32:33] op_sel_hi:[1,0]
	v_pk_mul_f32 v[56:57], v[56:57], v[32:33] op_sel_hi:[1,0]
	s_branch .LBB0_362

.LBB0_381:
	v_pk_add_f32 v[58:59], v[58:59], v[168:169] op_sel_hi:[1,0] neg_lo:[0,1] neg_hi:[0,1]
	v_pk_add_f32 v[56:57], v[56:57], v[168:169] op_sel_hi:[1,0] neg_lo:[0,1] neg_hi:[0,1]
	v_pk_add_f32 v[60:61], v[60:61], v[168:169] op_sel_hi:[1,0] neg_lo:[0,1] neg_hi:[0,1]
	v_pk_add_f32 v[62:63], v[62:63], v[168:169] op_sel_hi:[1,0] neg_lo:[0,1] neg_hi:[0,1]
	v_exp_f32_e32 v58, v58
	v_exp_f32_e32 v59, v59
	v_exp_f32_e32 v56, v56
	v_exp_f32_e32 v57, v57
	v_exp_f32_e32 v60, v60
	v_exp_f32_e32 v61, v61
	v_exp_f32_e32 v62, v62
	v_exp_f32_e32 v63, v63
	v_mov_b32_e32 v37, v36
	v_mov_b32_e32 v38, v36
	v_mov_b32_e32 v39, v36
	v_cvt_pk_bf16_f32 v59, v58, v59
	v_cvt_pk_bf16_f32 v58, v56, v57
	v_cvt_pk_bf16_f32 v56, v60, v61
	v_cvt_pk_bf16_f32 v57, v62, v63
	s_nop 1
	s_setprio 1
	v_mfma_f32_16x16x32_bf16 v[84:87], v[40:43], v[56:59], v[84:87]
	v_mfma_f32_16x16x32_bf16 v[80:83], v[44:47], v[56:59], v[80:83]
	v_mfma_f32_16x16x32_bf16 v[76:79], v[48:51], v[56:59], v[76:79]
	v_mfma_f32_16x16x32_bf16 v[72:75], v[52:55], v[56:59], v[72:75]
	v_mfma_f32_16x16x32_bf16 v[88:91], v[36:39], v[56:59], v[88:91]
	s_setprio 0
	s_add_i32 s25, s25, 2
	s_add_u32 s26, s26, 0x10000
	s_addc_u32 s27, s27, 0
	s_add_u32 s34, s34, 0x10000
	s_addc_u32 s35, s35, 0
	s_cmp_lt_u32 s30, 6
	s_cbranch_scc0 .LBB0_398
.LBB0_382:
	ds_read_b128 v[48:51], v167 offset:20480
	v_lshl_add_u64 v[34:35], s[34:35], 0, v[160:161]
	s_mov_b32 s0, 0x12708000
	v_add_co_u32_e32 v38, vcc, s0, v34
	s_mov_b32 s0, 0x1270c000
	s_nop 0
	v_addc_co_u32_e32 v39, vcc, 0, v35, vcc
	global_load_dwordx4 v[64:67], v[38:39], off
	global_load_dwordx4 v[60:63], v[38:39], off offset:1024
	ds_read_b128 v[156:159], v167 offset:21504
	s_waitcnt vmcnt(9) lgkmcnt(1)
	s_setprio 1
	v_mfma_f32_16x16x32_bf16 v[38:41], v[20:23], v[48:51], 0
	s_setprio 0
	v_add_co_u32_e32 v34, vcc, s0, v34
	v_lshl_add_u64 v[52:53], s[26:27], 0, v[160:161]
	s_nop 0
	v_addc_co_u32_e32 v35, vcc, 0, v35, vcc
	s_waitcnt vmcnt(8) lgkmcnt(0)
	s_setprio 1
	v_mfma_f32_16x16x32_bf16 v[152:155], v[16:19], v[156:159], v[38:41]
	s_setprio 0
	global_load_dwordx4 v[68:71], v[34:35], off
	global_load_dwordx4 v[56:59], v[34:35], off offset:1024
	s_nop 0
	global_load_dwordx4 v[40:43], v[52:53], off offset:-2048
	global_load_dwordx4 v[44:47], v[52:53], off offset:-1024
	s_nop 2
	s_waitcnt vmcnt(11)
	s_setprio 1
	v_mfma_f32_16x16x32_bf16 v[172:175], v[28:31], v[48:51], 0
	s_setprio 0
	global_load_dwordx4 v[48:51], v[52:53], off
	s_nop 0
	global_load_dwordx4 v[52:55], v[52:53], off offset:1024
	s_waitcnt vmcnt(12)
	s_setprio 1
	v_mfma_f32_16x16x32_bf16 v[156:159], v[24:27], v[156:159], v[172:175]
	s_nop 4
	s_setprio 0
	v_max3_f32 v32, v152, v153, v154
	s_nop 1
	v_max3_f32 v35, v155, v156, v157
	v_max3_f32 v32, v32, v158, v159
	v_max_f32_e32 v32, v32, v35
	v_add_f32_e32 v34, 0x41000000, v171
	v_cmp_gt_f32_e32 vcc, v32, v34
	s_cbranch_vccz .LBB0_384
	v_mov_b32_e32 v34, v32
	s_nop 1
	v_permlane16_swap_b32 v32, v34
	s_nop 0
	v_max_f32_e32 v34, v34, v34
	v_max_f32_e32 v32, v32, v32
	v_max_f32_e32 v32, v32, v34
	v_mov_b32_e32 v34, v32
	s_nop 1
	v_permlane32_swap_b32 v34, v32
	s_nop 0
	v_max3_f32 v34, v171, v34, v32
	v_sub_f32_e32 v32, v171, v34
	v_exp_f32_e32 v32, v32
	v_mov_b32_e32 v171, v34
	v_pk_mul_f32 v[146:147], v[146:147], v[32:33] op_sel_hi:[1,0]
	v_pk_mul_f32 v[144:145], v[144:145], v[32:33] op_sel_hi:[1,0]
	v_pk_mul_f32 v[142:143], v[142:143], v[32:33] op_sel_hi:[1,0]
	v_pk_mul_f32 v[140:141], v[140:141], v[32:33] op_sel_hi:[1,0]
	v_pk_mul_f32 v[138:139], v[138:139], v[32:33] op_sel_hi:[1,0]
	v_pk_mul_f32 v[136:137], v[136:137], v[32:33] op_sel_hi:[1,0]
	v_pk_mul_f32 v[134:135], v[134:135], v[32:33] op_sel_hi:[1,0]
	v_pk_mul_f32 v[132:133], v[132:133], v[32:33] op_sel_hi:[1,0]
	v_pk_mul_f32 v[150:151], v[150:151], v[32:33] op_sel_hi:[1,0]
	v_pk_mul_f32 v[148:149], v[148:149], v[32:33] op_sel_hi:[1,0]
.LBB0_384:
	v_pk_add_f32 v[152:153], v[152:153], v[170:171] op_sel:[0,1] op_sel_hi:[1,1] neg_lo:[0,1] neg_hi:[0,1]
	v_pk_add_f32 v[154:155], v[154:155], v[170:171] op_sel:[0,1] op_sel_hi:[1,1] neg_lo:[0,1] neg_hi:[0,1]
	v_pk_add_f32 v[156:157], v[156:157], v[170:171] op_sel:[0,1] op_sel_hi:[1,1] neg_lo:[0,1] neg_hi:[0,1]
	v_pk_add_f32 v[158:159], v[158:159], v[170:171] op_sel:[0,1] op_sel_hi:[1,1] neg_lo:[0,1] neg_hi:[0,1]
	v_exp_f32_e32 v152, v152
	v_exp_f32_e32 v153, v153
	v_exp_f32_e32 v154, v154
	v_exp_f32_e32 v155, v155
	v_exp_f32_e32 v156, v156
	v_exp_f32_e32 v157, v157
	v_exp_f32_e32 v158, v158
	v_exp_f32_e32 v159, v159
	v_mov_b32_e32 v37, v36
	v_mov_b32_e32 v38, v36
	v_mov_b32_e32 v39, v36
	v_cvt_pk_bf16_f32 v152, v152, v153
	v_cvt_pk_bf16_f32 v153, v154, v155
	v_cvt_pk_bf16_f32 v154, v156, v157
	v_cvt_pk_bf16_f32 v155, v158, v159
	s_waitcnt vmcnt(11)
	s_nop 0
	s_setprio 1
	v_mfma_f32_16x16x32_bf16 v[144:147], v[0:3], v[152:155], v[144:147]
	s_waitcnt vmcnt(10)
	v_mfma_f32_16x16x32_bf16 v[140:143], v[4:7], v[152:155], v[140:143]
	s_waitcnt vmcnt(9)
	v_mfma_f32_16x16x32_bf16 v[136:139], v[8:11], v[152:155], v[136:139]
	s_waitcnt vmcnt(8)
	v_mfma_f32_16x16x32_bf16 v[132:135], v[12:15], v[152:155], v[132:135]
	v_mfma_f32_16x16x32_bf16 v[148:151], v[36:39], v[152:155], v[148:151]
	s_setprio 0
	ds_read_b128 v[152:155], v167 offset:22528
	ds_read_b128 v[172:175], v167 offset:23552
	s_waitcnt lgkmcnt(1)
	s_setprio 1
	v_mfma_f32_16x16x32_bf16 v[156:159], v[20:23], v[152:155], 0
	v_mfma_f32_16x16x32_bf16 v[152:155], v[28:31], v[152:155], 0
	s_waitcnt lgkmcnt(0)
	v_mfma_f32_16x16x32_bf16 v[156:159], v[16:19], v[172:175], v[156:159]
	v_mfma_f32_16x16x32_bf16 v[152:155], v[24:27], v[172:175], v[152:155]
	s_nop 6
	s_setprio 0
	v_max3_f32 v32, v156, v157, v158
	v_max3_f32 v35, v159, v152, v153
	v_max3_f32 v32, v32, v154, v155
	v_max_f32_e32 v32, v32, v35
	v_add_f32_e32 v34, 0x41000000, v170
	v_cmp_gt_f32_e32 vcc, v32, v34
	s_cbranch_vccz .LBB0_386
	v_mov_b32_e32 v34, v32
	s_nop 1
	v_permlane16_swap_b32 v32, v34
	s_nop 0
	v_max_f32_e32 v34, v34, v34
	v_max_f32_e32 v32, v32, v32
	v_max_f32_e32 v32, v32, v34
	v_mov_b32_e32 v34, v32
	s_nop 1
	v_permlane32_swap_b32 v32, v34
	s_nop 0
	v_max3_f32 v34, v170, v32, v34
	v_sub_f32_e32 v32, v170, v34
	v_exp_f32_e32 v32, v32
	v_mov_b32_e32 v170, v34
	v_pk_mul_f32 v[126:127], v[126:127], v[32:33] op_sel_hi:[1,0]
	v_pk_mul_f32 v[124:125], v[124:125], v[32:33] op_sel_hi:[1,0]
	v_pk_mul_f32 v[122:123], v[122:123], v[32:33] op_sel_hi:[1,0]
	v_pk_mul_f32 v[120:121], v[120:121], v[32:33] op_sel_hi:[1,0]
	v_pk_mul_f32 v[118:119], v[118:119], v[32:33] op_sel_hi:[1,0]
	v_pk_mul_f32 v[116:117], v[116:117], v[32:33] op_sel_hi:[1,0]
	v_pk_mul_f32 v[114:115], v[114:115], v[32:33] op_sel_hi:[1,0]
	v_pk_mul_f32 v[112:113], v[112:113], v[32:33] op_sel_hi:[1,0]
	v_pk_mul_f32 v[130:131], v[130:131], v[32:33] op_sel_hi:[1,0]
	v_pk_mul_f32 v[128:129], v[128:129], v[32:33] op_sel_hi:[1,0]
.LBB0_386:
	v_pk_add_f32 v[154:155], v[154:155], v[170:171] op_sel_hi:[1,0] neg_lo:[0,1] neg_hi:[0,1]
	v_pk_add_f32 v[152:153], v[152:153], v[170:171] op_sel_hi:[1,0] neg_lo:[0,1] neg_hi:[0,1]
	v_pk_add_f32 v[156:157], v[156:157], v[170:171] op_sel_hi:[1,0] neg_lo:[0,1] neg_hi:[0,1]
	v_pk_add_f32 v[158:159], v[158:159], v[170:171] op_sel_hi:[1,0] neg_lo:[0,1] neg_hi:[0,1]
	v_exp_f32_e32 v154, v154
	v_exp_f32_e32 v155, v155
	v_exp_f32_e32 v152, v152
	v_exp_f32_e32 v153, v153
	v_exp_f32_e32 v156, v156
	v_exp_f32_e32 v157, v157
	v_exp_f32_e32 v158, v158
	v_exp_f32_e32 v159, v159
	v_cvt_pk_bf16_f32 v155, v154, v155
	v_cvt_pk_bf16_f32 v154, v152, v153
	v_cvt_pk_bf16_f32 v152, v156, v157
	v_cvt_pk_bf16_f32 v153, v158, v159
	s_nop 1
	s_setprio 1
	v_mfma_f32_16x16x32_bf16 v[124:127], v[0:3], v[152:155], v[124:127]
	v_mfma_f32_16x16x32_bf16 v[120:123], v[4:7], v[152:155], v[120:123]
	v_mfma_f32_16x16x32_bf16 v[116:119], v[8:11], v[152:155], v[116:119]
	v_mfma_f32_16x16x32_bf16 v[112:115], v[12:15], v[152:155], v[112:115]
	v_mfma_f32_16x16x32_bf16 v[128:131], v[36:39], v[152:155], v[128:131]
	s_setprio 0
	ds_read_b128 v[152:155], v167 offset:24576
	ds_read_b128 v[172:175], v167 offset:25600
	s_waitcnt lgkmcnt(1)
	s_setprio 1
	v_mfma_f32_16x16x32_bf16 v[156:159], v[20:23], v[152:155], 0
	v_mfma_f32_16x16x32_bf16 v[152:155], v[28:31], v[152:155], 0
	s_waitcnt lgkmcnt(0)
	v_mfma_f32_16x16x32_bf16 v[156:159], v[16:19], v[172:175], v[156:159]
	v_mfma_f32_16x16x32_bf16 v[152:155], v[24:27], v[172:175], v[152:155]
	s_nop 6
	s_setprio 0
	v_max3_f32 v32, v156, v157, v158
	v_max3_f32 v35, v159, v152, v153
	v_max3_f32 v32, v32, v154, v155
	v_max_f32_e32 v32, v32, v35
	v_add_f32_e32 v34, 0x41000000, v169
	v_cmp_gt_f32_e32 vcc, v32, v34
	s_cbranch_vccz .LBB0_388
	v_mov_b32_e32 v34, v32
	s_nop 1
	v_permlane16_swap_b32 v32, v34
	s_nop 0
	v_max_f32_e32 v34, v34, v34
	v_max_f32_e32 v32, v32, v32
	v_max_f32_e32 v32, v32, v34
	v_mov_b32_e32 v34, v32
	s_nop 1
	v_permlane32_swap_b32 v32, v34
	s_nop 0
	v_max3_f32 v34, v169, v32, v34
	v_sub_f32_e32 v32, v169, v34
	v_exp_f32_e32 v32, v32
	v_mov_b32_e32 v169, v34
	v_pk_mul_f32 v[106:107], v[106:107], v[32:33] op_sel_hi:[1,0]
	v_pk_mul_f32 v[104:105], v[104:105], v[32:33] op_sel_hi:[1,0]
	v_pk_mul_f32 v[102:103], v[102:103], v[32:33] op_sel_hi:[1,0]
	v_pk_mul_f32 v[100:101], v[100:101], v[32:33] op_sel_hi:[1,0]
	v_pk_mul_f32 v[98:99], v[98:99], v[32:33] op_sel_hi:[1,0]
	v_pk_mul_f32 v[96:97], v[96:97], v[32:33] op_sel_hi:[1,0]
	v_pk_mul_f32 v[94:95], v[94:95], v[32:33] op_sel_hi:[1,0]
	v_pk_mul_f32 v[92:93], v[92:93], v[32:33] op_sel_hi:[1,0]
	v_pk_mul_f32 v[110:111], v[110:111], v[32:33] op_sel_hi:[1,0]
	v_pk_mul_f32 v[108:109], v[108:109], v[32:33] op_sel_hi:[1,0]
.LBB0_388:
	v_pk_add_f32 v[154:155], v[154:155], v[168:169] op_sel:[0,1] op_sel_hi:[1,1] neg_lo:[0,1] neg_hi:[0,1]
	v_pk_add_f32 v[152:153], v[152:153], v[168:169] op_sel:[0,1] op_sel_hi:[1,1] neg_lo:[0,1] neg_hi:[0,1]
	v_pk_add_f32 v[156:157], v[156:157], v[168:169] op_sel:[0,1] op_sel_hi:[1,1] neg_lo:[0,1] neg_hi:[0,1]
	v_pk_add_f32 v[158:159], v[158:159], v[168:169] op_sel:[0,1] op_sel_hi:[1,1] neg_lo:[0,1] neg_hi:[0,1]
	v_exp_f32_e32 v154, v154
	v_exp_f32_e32 v155, v155
	v_exp_f32_e32 v152, v152
	v_exp_f32_e32 v153, v153
	v_exp_f32_e32 v156, v156
	v_exp_f32_e32 v157, v157
	v_exp_f32_e32 v158, v158
	v_exp_f32_e32 v159, v159
	v_cvt_pk_bf16_f32 v155, v154, v155
	v_cvt_pk_bf16_f32 v154, v152, v153
	v_cvt_pk_bf16_f32 v152, v156, v157
	v_cvt_pk_bf16_f32 v153, v158, v159
	s_nop 1
	s_setprio 1
	v_mfma_f32_16x16x32_bf16 v[104:107], v[0:3], v[152:155], v[104:107]
	v_mfma_f32_16x16x32_bf16 v[100:103], v[4:7], v[152:155], v[100:103]
	v_mfma_f32_16x16x32_bf16 v[96:99], v[8:11], v[152:155], v[96:99]
	v_mfma_f32_16x16x32_bf16 v[92:95], v[12:15], v[152:155], v[92:95]
	v_mfma_f32_16x16x32_bf16 v[108:111], v[36:39], v[152:155], v[108:111]
	s_setprio 0
	ds_read_b128 v[152:155], v167 offset:26624
	s_waitcnt lgkmcnt(0)
	s_setprio 1
	v_mfma_f32_16x16x32_bf16 v[20:23], v[20:23], v[152:155], 0
	v_mfma_f32_16x16x32_bf16 v[28:31], v[28:31], v[152:155], 0
	s_setprio 0
	ds_read_b128 v[152:155], v167 offset:27648
	s_waitcnt lgkmcnt(0)
	s_setprio 1
	v_mfma_f32_16x16x32_bf16 v[16:19], v[16:19], v[152:155], v[20:23]
	s_nop 7
	v_mfma_f32_16x16x32_bf16 v[20:23], v[24:27], v[152:155], v[28:31]
	s_nop 7
	s_setprio 0
	v_max3_f32 v24, v16, v17, v18
	v_max3_f32 v25, v19, v20, v21
	v_max3_f32 v24, v24, v22, v23
	v_max_f32_e32 v24, v24, v25
	v_add_f32_e32 v25, 0x41000000, v168
	v_cmp_gt_f32_e32 vcc, v24, v25
	s_cbranch_vccz .LBB0_390
	v_mov_b32_e32 v25, v24
	s_nop 1
	v_permlane16_swap_b32 v24, v25
	s_nop 0
	v_max_f32_e32 v25, v25, v25
	v_max_f32_e32 v24, v24, v24
	v_max_f32_e32 v24, v24, v25
	v_mov_b32_e32 v25, v24
	s_nop 1
	v_permlane32_swap_b32 v24, v25
	s_nop 0
	v_max3_f32 v25, v168, v24, v25
	v_sub_f32_e32 v24, v168, v25
	v_exp_f32_e32 v24, v24
	v_mov_b32_e32 v168, v25
	v_pk_mul_f32 v[86:87], v[86:87], v[24:25] op_sel_hi:[1,0]
	v_pk_mul_f32 v[84:85], v[84:85], v[24:25] op_sel_hi:[1,0]
	v_pk_mul_f32 v[82:83], v[82:83], v[24:25] op_sel_hi:[1,0]
	v_pk_mul_f32 v[80:81], v[80:81], v[24:25] op_sel_hi:[1,0]
	v_pk_mul_f32 v[78:79], v[78:79], v[24:25] op_sel_hi:[1,0]
	v_pk_mul_f32 v[76:77], v[76:77], v[24:25] op_sel_hi:[1,0]
	v_pk_mul_f32 v[74:75], v[74:75], v[24:25] op_sel_hi:[1,0]
	v_pk_mul_f32 v[72:73], v[72:73], v[24:25] op_sel_hi:[1,0]
	v_pk_mul_f32 v[90:91], v[90:91], v[24:25] op_sel_hi:[1,0]
	v_pk_mul_f32 v[88:89], v[88:89], v[24:25] op_sel_hi:[1,0]
.LBB0_390:
	v_pk_add_f32 v[16:17], v[16:17], v[168:169] op_sel_hi:[1,0] neg_lo:[0,1] neg_hi:[0,1]
	v_pk_add_f32 v[18:19], v[18:19], v[168:169] op_sel_hi:[1,0] neg_lo:[0,1] neg_hi:[0,1]
	v_pk_add_f32 v[20:21], v[20:21], v[168:169] op_sel_hi:[1,0] neg_lo:[0,1] neg_hi:[0,1]
	v_pk_add_f32 v[22:23], v[22:23], v[168:169] op_sel_hi:[1,0] neg_lo:[0,1] neg_hi:[0,1]
	v_exp_f32_e32 v16, v16
	v_exp_f32_e32 v17, v17
	v_exp_f32_e32 v18, v18
	v_exp_f32_e32 v19, v19
	v_exp_f32_e32 v20, v20
	v_exp_f32_e32 v21, v21
	v_exp_f32_e32 v22, v22
	v_exp_f32_e32 v23, v23
	v_cvt_pk_bf16_f32 v16, v16, v17
	v_cvt_pk_bf16_f32 v17, v18, v19
	v_cvt_pk_bf16_f32 v18, v20, v21
	v_cvt_pk_bf16_f32 v19, v22, v23
	s_add_i32 s30, s25, -2
	s_nop 0
	s_setprio 1
	v_mfma_f32_16x16x32_bf16 v[84:87], v[0:3], v[16:19], v[84:87]
	v_mfma_f32_16x16x32_bf16 v[80:83], v[4:7], v[16:19], v[80:83]
	v_mfma_f32_16x16x32_bf16 v[76:79], v[8:11], v[16:19], v[76:79]
	v_mfma_f32_16x16x32_bf16 v[72:75], v[12:15], v[16:19], v[72:75]
	v_mfma_f32_16x16x32_bf16 v[88:91], v[36:39], v[16:19], v[88:91]
	s_setprio 0
	s_cmp_lt_u32 s30, 6
	s_cselect_b32 s0, s25, 0
	s_add_i32 s40, s0, s60
	ds_read_b128 v[8:11], v167 offset:20480
	s_lshl_b32 s0, s40, 1
	s_lshl_b64 s[42:43], s[0:1], 14
	v_lshl_add_u64 v[4:5], v[162:163], 0, s[42:43]
	global_load_dwordx4 v[20:23], v[4:5], off
	global_load_dwordx4 v[16:19], v[4:5], off offset:1024
	ds_read_b128 v[156:159], v167 offset:21504
	s_waitcnt vmcnt(9) lgkmcnt(1)
	s_setprio 1
	v_mfma_f32_16x16x32_bf16 v[0:3], v[64:67], v[8:11], 0
	s_setprio 0
	s_mov_b32 s41, s1
	v_add_co_u32_e32 v4, vcc, s72, v4
	s_lshl_b64 s[40:41], s[40:41], 15
	s_nop 0
	v_addc_co_u32_e32 v5, vcc, 0, v5, vcc
	v_lshl_add_u64 v[12:13], v[164:165], 0, s[40:41]
	s_waitcnt vmcnt(8) lgkmcnt(0)
	s_setprio 1
	v_mfma_f32_16x16x32_bf16 v[152:155], v[60:63], v[156:159], v[0:3]
	s_setprio 0
	global_load_dwordx4 v[28:31], v[4:5], off
	global_load_dwordx4 v[24:27], v[4:5], off offset:1024
	s_nop 0
	global_load_dwordx4 v[0:3], v[12:13], off
	global_load_dwordx4 v[4:7], v[12:13], off offset:1024
	s_nop 2
	s_waitcnt vmcnt(11)
	s_setprio 1
	v_mfma_f32_16x16x32_bf16 v[172:175], v[68:71], v[8:11], 0
	s_setprio 0
	global_load_dwordx4 v[8:11], v[12:13], off offset:2048
	s_nop 0
	global_load_dwordx4 v[12:15], v[12:13], off offset:3072
	s_waitcnt vmcnt(12)
	s_setprio 1
	v_mfma_f32_16x16x32_bf16 v[156:159], v[56:59], v[156:159], v[172:175]
	s_nop 4
	s_setprio 0
	v_max3_f32 v32, v152, v153, v154
	s_nop 1
	v_max3_f32 v35, v155, v156, v157
	v_max3_f32 v32, v32, v158, v159
	v_max_f32_e32 v32, v32, v35
	v_add_f32_e32 v34, 0x41000000, v171
	v_cmp_gt_f32_e32 vcc, v32, v34
	s_cbranch_vccz .LBB0_392
	v_mov_b32_e32 v34, v32
	s_nop 1
	v_permlane16_swap_b32 v32, v34
	s_nop 0
	v_max_f32_e32 v34, v34, v34
	v_max_f32_e32 v32, v32, v32
	v_max_f32_e32 v32, v32, v34
	v_mov_b32_e32 v34, v32
	s_nop 1
	v_permlane32_swap_b32 v32, v34
	s_nop 0
	v_max3_f32 v34, v171, v32, v34
	v_sub_f32_e32 v32, v171, v34
	v_exp_f32_e32 v32, v32
	v_mov_b32_e32 v171, v34
	v_pk_mul_f32 v[146:147], v[146:147], v[32:33] op_sel_hi:[1,0]
	v_pk_mul_f32 v[144:145], v[144:145], v[32:33] op_sel_hi:[1,0]
	v_pk_mul_f32 v[142:143], v[142:143], v[32:33] op_sel_hi:[1,0]
	v_pk_mul_f32 v[140:141], v[140:141], v[32:33] op_sel_hi:[1,0]
	v_pk_mul_f32 v[138:139], v[138:139], v[32:33] op_sel_hi:[1,0]
	v_pk_mul_f32 v[136:137], v[136:137], v[32:33] op_sel_hi:[1,0]
	v_pk_mul_f32 v[134:135], v[134:135], v[32:33] op_sel_hi:[1,0]
	v_pk_mul_f32 v[132:133], v[132:133], v[32:33] op_sel_hi:[1,0]
	v_pk_mul_f32 v[150:151], v[150:151], v[32:33] op_sel_hi:[1,0]
	v_pk_mul_f32 v[148:149], v[148:149], v[32:33] op_sel_hi:[1,0]
.LBB0_392:
	v_pk_add_f32 v[152:153], v[152:153], v[170:171] op_sel:[0,1] op_sel_hi:[1,1] neg_lo:[0,1] neg_hi:[0,1]
	v_pk_add_f32 v[154:155], v[154:155], v[170:171] op_sel:[0,1] op_sel_hi:[1,1] neg_lo:[0,1] neg_hi:[0,1]
	v_pk_add_f32 v[156:157], v[156:157], v[170:171] op_sel:[0,1] op_sel_hi:[1,1] neg_lo:[0,1] neg_hi:[0,1]
	v_pk_add_f32 v[158:159], v[158:159], v[170:171] op_sel:[0,1] op_sel_hi:[1,1] neg_lo:[0,1] neg_hi:[0,1]
	v_exp_f32_e32 v152, v152
	v_exp_f32_e32 v153, v153
	v_exp_f32_e32 v154, v154
	v_exp_f32_e32 v155, v155
	v_exp_f32_e32 v156, v156
	v_exp_f32_e32 v157, v157
	v_exp_f32_e32 v158, v158
	v_exp_f32_e32 v159, v159
	v_cvt_pk_bf16_f32 v152, v152, v153
	v_cvt_pk_bf16_f32 v153, v154, v155
	v_cvt_pk_bf16_f32 v154, v156, v157
	v_cvt_pk_bf16_f32 v155, v158, v159
	s_waitcnt vmcnt(11)
	s_nop 0
	s_setprio 1
	v_mfma_f32_16x16x32_bf16 v[144:147], v[40:43], v[152:155], v[144:147]
	s_waitcnt vmcnt(10)
	v_mfma_f32_16x16x32_bf16 v[140:143], v[44:47], v[152:155], v[140:143]
	s_waitcnt vmcnt(9)
	v_mfma_f32_16x16x32_bf16 v[136:139], v[48:51], v[152:155], v[136:139]
	s_waitcnt vmcnt(8)
	v_mfma_f32_16x16x32_bf16 v[132:135], v[52:55], v[152:155], v[132:135]
	v_mfma_f32_16x16x32_bf16 v[148:151], v[36:39], v[152:155], v[148:151]
	s_setprio 0
	ds_read_b128 v[152:155], v167 offset:22528
	ds_read_b128 v[172:175], v167 offset:23552
	s_waitcnt lgkmcnt(1)
	s_setprio 1
	v_mfma_f32_16x16x32_bf16 v[156:159], v[64:67], v[152:155], 0
	v_mfma_f32_16x16x32_bf16 v[152:155], v[68:71], v[152:155], 0
	s_waitcnt lgkmcnt(0)
	v_mfma_f32_16x16x32_bf16 v[156:159], v[60:63], v[172:175], v[156:159]
	v_mfma_f32_16x16x32_bf16 v[152:155], v[56:59], v[172:175], v[152:155]
	s_nop 6
	s_setprio 0
	v_max3_f32 v32, v156, v157, v158
	v_max3_f32 v35, v159, v152, v153
	v_max3_f32 v32, v32, v154, v155
	v_max_f32_e32 v32, v32, v35
	v_add_f32_e32 v34, 0x41000000, v170
	v_cmp_gt_f32_e32 vcc, v32, v34
	s_cbranch_vccz .LBB0_394
	v_mov_b32_e32 v34, v32
	s_nop 1
	v_permlane16_swap_b32 v32, v34
	s_nop 0
	v_max_f32_e32 v34, v34, v34
	v_max_f32_e32 v32, v32, v32
	v_max_f32_e32 v32, v32, v34
	v_mov_b32_e32 v34, v32
	s_nop 1
	v_permlane32_swap_b32 v32, v34
	s_nop 0
	v_max3_f32 v34, v170, v32, v34
	v_sub_f32_e32 v32, v170, v34
	v_exp_f32_e32 v32, v32
	v_mov_b32_e32 v170, v34
	v_pk_mul_f32 v[126:127], v[126:127], v[32:33] op_sel_hi:[1,0]
	v_pk_mul_f32 v[124:125], v[124:125], v[32:33] op_sel_hi:[1,0]
	v_pk_mul_f32 v[122:123], v[122:123], v[32:33] op_sel_hi:[1,0]
	v_pk_mul_f32 v[120:121], v[120:121], v[32:33] op_sel_hi:[1,0]
	v_pk_mul_f32 v[118:119], v[118:119], v[32:33] op_sel_hi:[1,0]
	v_pk_mul_f32 v[116:117], v[116:117], v[32:33] op_sel_hi:[1,0]
	v_pk_mul_f32 v[114:115], v[114:115], v[32:33] op_sel_hi:[1,0]
	v_pk_mul_f32 v[112:113], v[112:113], v[32:33] op_sel_hi:[1,0]
	v_pk_mul_f32 v[130:131], v[130:131], v[32:33] op_sel_hi:[1,0]
	v_pk_mul_f32 v[128:129], v[128:129], v[32:33] op_sel_hi:[1,0]
.LBB0_394:
	v_pk_add_f32 v[154:155], v[154:155], v[170:171] op_sel_hi:[1,0] neg_lo:[0,1] neg_hi:[0,1]
	v_pk_add_f32 v[152:153], v[152:153], v[170:171] op_sel_hi:[1,0] neg_lo:[0,1] neg_hi:[0,1]
	v_pk_add_f32 v[156:157], v[156:157], v[170:171] op_sel_hi:[1,0] neg_lo:[0,1] neg_hi:[0,1]
	v_pk_add_f32 v[158:159], v[158:159], v[170:171] op_sel_hi:[1,0] neg_lo:[0,1] neg_hi:[0,1]
	v_exp_f32_e32 v154, v154
	v_exp_f32_e32 v155, v155
	v_exp_f32_e32 v152, v152
	v_exp_f32_e32 v153, v153
	v_exp_f32_e32 v156, v156
	v_exp_f32_e32 v157, v157
	v_exp_f32_e32 v158, v158
	v_exp_f32_e32 v159, v159
	v_cvt_pk_bf16_f32 v155, v154, v155
	v_cvt_pk_bf16_f32 v154, v152, v153
	v_cvt_pk_bf16_f32 v152, v156, v157
	v_cvt_pk_bf16_f32 v153, v158, v159
	s_nop 1
	s_setprio 1
	v_mfma_f32_16x16x32_bf16 v[124:127], v[40:43], v[152:155], v[124:127]
	v_mfma_f32_16x16x32_bf16 v[120:123], v[44:47], v[152:155], v[120:123]
	v_mfma_f32_16x16x32_bf16 v[116:119], v[48:51], v[152:155], v[116:119]
	v_mfma_f32_16x16x32_bf16 v[112:115], v[52:55], v[152:155], v[112:115]
	v_mfma_f32_16x16x32_bf16 v[128:131], v[36:39], v[152:155], v[128:131]
	s_setprio 0
	ds_read_b128 v[152:155], v167 offset:24576
	ds_read_b128 v[172:175], v167 offset:25600
	s_waitcnt lgkmcnt(1)
	s_setprio 1
	v_mfma_f32_16x16x32_bf16 v[156:159], v[64:67], v[152:155], 0
	v_mfma_f32_16x16x32_bf16 v[152:155], v[68:71], v[152:155], 0
	s_waitcnt lgkmcnt(0)
	v_mfma_f32_16x16x32_bf16 v[156:159], v[60:63], v[172:175], v[156:159]
	v_mfma_f32_16x16x32_bf16 v[152:155], v[56:59], v[172:175], v[152:155]
	s_nop 6
	s_setprio 0
	v_max3_f32 v32, v156, v157, v158
	v_max3_f32 v35, v159, v152, v153
	v_max3_f32 v32, v32, v154, v155
	v_max_f32_e32 v32, v32, v35
	v_add_f32_e32 v34, 0x41000000, v169
	v_cmp_gt_f32_e32 vcc, v32, v34
	s_cbranch_vccz .LBB0_396
	v_mov_b32_e32 v34, v32
	s_nop 1
	v_permlane16_swap_b32 v32, v34
	s_nop 0
	v_max_f32_e32 v34, v34, v34
	v_max_f32_e32 v32, v32, v32
	v_max_f32_e32 v32, v32, v34
	v_mov_b32_e32 v34, v32
	s_nop 1
	v_permlane32_swap_b32 v34, v32
	s_nop 0
	v_max3_f32 v34, v169, v34, v32
	v_sub_f32_e32 v32, v169, v34
	v_exp_f32_e32 v32, v32
	v_mov_b32_e32 v169, v34
	v_pk_mul_f32 v[106:107], v[106:107], v[32:33] op_sel_hi:[1,0]
	v_pk_mul_f32 v[104:105], v[104:105], v[32:33] op_sel_hi:[1,0]
	v_pk_mul_f32 v[102:103], v[102:103], v[32:33] op_sel_hi:[1,0]
	v_pk_mul_f32 v[100:101], v[100:101], v[32:33] op_sel_hi:[1,0]
	v_pk_mul_f32 v[98:99], v[98:99], v[32:33] op_sel_hi:[1,0]
	v_pk_mul_f32 v[96:97], v[96:97], v[32:33] op_sel_hi:[1,0]
	v_pk_mul_f32 v[94:95], v[94:95], v[32:33] op_sel_hi:[1,0]
	v_pk_mul_f32 v[92:93], v[92:93], v[32:33] op_sel_hi:[1,0]
	v_pk_mul_f32 v[110:111], v[110:111], v[32:33] op_sel_hi:[1,0]
	v_pk_mul_f32 v[108:109], v[108:109], v[32:33] op_sel_hi:[1,0]
.LBB0_396:
	v_pk_add_f32 v[154:155], v[154:155], v[168:169] op_sel:[0,1] op_sel_hi:[1,1] neg_lo:[0,1] neg_hi:[0,1]
	v_pk_add_f32 v[152:153], v[152:153], v[168:169] op_sel:[0,1] op_sel_hi:[1,1] neg_lo:[0,1] neg_hi:[0,1]
	v_pk_add_f32 v[156:157], v[156:157], v[168:169] op_sel:[0,1] op_sel_hi:[1,1] neg_lo:[0,1] neg_hi:[0,1]
	v_pk_add_f32 v[158:159], v[158:159], v[168:169] op_sel:[0,1] op_sel_hi:[1,1] neg_lo:[0,1] neg_hi:[0,1]
	v_exp_f32_e32 v154, v154
	v_exp_f32_e32 v155, v155
	v_exp_f32_e32 v152, v152
	v_exp_f32_e32 v153, v153
	v_exp_f32_e32 v156, v156
	v_exp_f32_e32 v157, v157
	v_exp_f32_e32 v158, v158
	v_exp_f32_e32 v159, v159
	v_cvt_pk_bf16_f32 v155, v154, v155
	v_cvt_pk_bf16_f32 v154, v152, v153
	v_cvt_pk_bf16_f32 v152, v156, v157
	v_cvt_pk_bf16_f32 v153, v158, v159
	s_nop 1
	s_setprio 1
	v_mfma_f32_16x16x32_bf16 v[104:107], v[40:43], v[152:155], v[104:107]
	v_mfma_f32_16x16x32_bf16 v[100:103], v[44:47], v[152:155], v[100:103]
	v_mfma_f32_16x16x32_bf16 v[96:99], v[48:51], v[152:155], v[96:99]
	v_mfma_f32_16x16x32_bf16 v[92:95], v[52:55], v[152:155], v[92:95]
	v_mfma_f32_16x16x32_bf16 v[108:111], v[36:39], v[152:155], v[108:111]
	s_setprio 0
	ds_read_b128 v[152:155], v167 offset:26624
	s_waitcnt lgkmcnt(0)
	s_setprio 1
	v_mfma_f32_16x16x32_bf16 v[64:67], v[64:67], v[152:155], 0
	v_mfma_f32_16x16x32_bf16 v[68:71], v[68:71], v[152:155], 0
	s_setprio 0
	ds_read_b128 v[152:155], v167 offset:27648
	s_waitcnt lgkmcnt(0)
	s_setprio 1
	v_mfma_f32_16x16x32_bf16 v[60:63], v[60:63], v[152:155], v[64:67]
	v_mfma_f32_16x16x32_bf16 v[56:59], v[56:59], v[152:155], v[68:71]
	s_nop 6
	s_setprio 0
	v_max3_f32 v32, v60, v61, v62
	v_max3_f32 v35, v63, v56, v57
	v_max3_f32 v32, v32, v58, v59
	v_max_f32_e32 v32, v32, v35
	v_add_f32_e32 v34, 0x41000000, v168
	v_cmp_gt_f32_e32 vcc, v32, v34
	s_cbranch_vccz .LBB0_381
	v_mov_b32_e32 v34, v32
	s_nop 1
	v_permlane16_swap_b32 v32, v34
	s_nop 0
	v_max_f32_e32 v34, v34, v34
	v_max_f32_e32 v32, v32, v32
	v_max_f32_e32 v32, v32, v34
	v_mov_b32_e32 v34, v32
	s_nop 1
	v_permlane32_swap_b32 v32, v34
	s_nop 0
	v_max3_f32 v34, v168, v32, v34
	v_sub_f32_e32 v32, v168, v34
	v_exp_f32_e32 v32, v32
	v_mov_b32_e32 v168, v34
	v_pk_mul_f32 v[86:87], v[86:87], v[32:33] op_sel_hi:[1,0]
	v_pk_mul_f32 v[84:85], v[84:85], v[32:33] op_sel_hi:[1,0]
	v_pk_mul_f32 v[82:83], v[82:83], v[32:33] op_sel_hi:[1,0]
	v_pk_mul_f32 v[80:81], v[80:81], v[32:33] op_sel_hi:[1,0]
	v_pk_mul_f32 v[78:79], v[78:79], v[32:33] op_sel_hi:[1,0]
	v_pk_mul_f32 v[76:77], v[76:77], v[32:33] op_sel_hi:[1,0]
	v_pk_mul_f32 v[74:75], v[74:75], v[32:33] op_sel_hi:[1,0]
	v_pk_mul_f32 v[72:73], v[72:73], v[32:33] op_sel_hi:[1,0]
	v_pk_mul_f32 v[90:91], v[90:91], v[32:33] op_sel_hi:[1,0]
	v_pk_mul_f32 v[88:89], v[88:89], v[32:33] op_sel_hi:[1,0]
	s_branch .LBB0_381
